# GEMM unit boundaries: ALIGN_EPI barrier (waves 0-3) removed together with the last post-MFMA barrier of waves 4-7 of each unit; the leading half runs its epilogue and next-unit load segment under the
# speedup vs baseline: 1.0027x; 1.0027x over previous
; #define PG8_STAGE(bufoff, gbase, voff) do { _Pragma("unroll") for (int _i = 0; _i < 2; ++_i) \
;         __builtin_amdgcn_global_load_lds((const unsigned*)((const char*)(gbase) + (voff)[_i]), (LAS unsigned*)(lds + (bufoff) + ldsw + _i * 8192), 16, 0, 0); } while (0)
; #define PG8_LDA(dst, b, h) do { _Pragma("unroll") for (int m = 0; m < 4; ++m) _Pragma("unroll") for (int k = 0; k < 2; ++k) dst[m][k] = *(const LAS bf16x8*)(lds + PG8_SA(b, h) + aoff + m * 2048 + k * 1024); } while (0)
; #define PG8_LDB(dst, b, h) do { _Pragma("unroll") for (int n = 0; n < 2; ++n) _Pragma("unroll") for (int k = 0; k < 2; ++k) dst[n][k] = *(const LAS bf16x8*)(lds + PG8_SB(b, h) + boff + n * 2048 + k * 1024); } while (0)
; #define PG8_WAIT_V(n) asm volatile("s_waitcnt vmcnt(" #n ")" ::: "memory")
; #define PG8_WAIT_L(n) asm volatile("s_waitcnt lgkmcnt(" #n ")" ::: "memory")
; #define PG8_BAR __builtin_amdgcn_s_barrier()
; #define PG8_SCHED __builtin_amdgcn_sched_barrier(0)
; template <class Epi, class Sched, bool I8 = false>
; __device__ __forceinline__ void gemm_phase(LAS unsigned char* lds, const Gemm g, const Sched& S, const Epi& E) {
;     ...
;             PG8_LDB(B0, 0, 0); PG8_LDB(B1, 0, 1); PG8_SCHED; PG8_LDA(At, 0, 0); PG8_STAGE(PG8_SA(1, 1), a1 + hstepA, voffA);
;             PG8_WAIT_V(8); PG8_WAIT_L(0); PG8_BAR; PG8_MMA(0, 0, At, B0); PG8_MMA(0, 1, At, B1); PG8_BAR; PG8_SCHED;
;             PG8_LDA(At, 0, 1); PG8_STAGE(PG8_SB(0, 0), b2, voffB); PG8_STAGE(PG8_SB(0, 1), b2 + hstepB, voffB); PG8_STAGE(PG8_SA(0, 0), a2, voffA);
;             PG8_WAIT_V(8); PG8_WAIT_L(0); PG8_BAR; PG8_MMA(1, 0, At, B0); PG8_MMA(1, 1, At, B1); PG8_BAR; PG8_SCHED;
.LBB0_1169:
	ds_read_b128 v[90:93], v169
	ds_read_b128 v[98:101], v169 offset:1024
	ds_read_b128 v[172:175], v169 offset:2048
	ds_read_b128 v[176:179], v169 offset:3072
	ds_read_b128 v[180:183], v170
	ds_read_b128 v[184:187], v170 offset:1024
	ds_read_b128 v[188:191], v170 offset:2048
	ds_read_b128 v[192:195], v170 offset:3072
	s_add_u32 s22, s20, 0x4000
	s_addc_u32 s23, s21, 0
	s_cmp_eq_u32 s53, 28
	s_cselect_b32 s26, s49, s22
	s_cselect_b32 s27, s13, s23
	s_cselect_b32 s24, s50, s51
	s_cselect_b32 s25, s11, s52
	s_add_u32 s22, s26, 0x8000
	s_addc_u32 s23, s27, 0
	s_sub_u32 s98, s20, 0x4000
	s_subb_u32 s99, s21, 0
	s_mov_b32 m0, s43
	s_nop 0
	global_load_lds_dwordx4 v144, s[98:99]
	s_mov_b32 m0, s44
	s_nop 0
	global_load_lds_dwordx4 v140, s[98:99]
	s_add_i32 m0, s36, 0xc000
	ds_read_b128 v[196:199], v171
	ds_read_b128 v[200:203], v171 offset:1024
	ds_read_b128 v[204:207], v171 offset:2048
	ds_read_b128 v[208:211], v171 offset:3072
	ds_read_b128 v[212:215], v171 offset:4096
	ds_read_b128 v[216:219], v171 offset:5120
	ds_read_b128 v[220:223], v171 offset:6144
	ds_read_b128 v[224:227], v171 offset:7168
	global_load_lds_dwordx4 v148, s[20:21]
	s_add_i32 m0, s36, 0xe000
	s_nop 0
	global_load_lds_dwordx4 v150, s[20:21]
	s_waitcnt vmcnt(8)
	s_waitcnt lgkmcnt(0)
	s_barrier
	s_waitcnt lgkmcnt(0)
	v_mfma_i32_16x16x64_i8 v[134:137], v[90:93], v[196:199], v[134:137]
	v_mfma_i32_16x16x64_i8 v[130:133], v[172:175], v[196:199], v[130:133]
	v_mfma_i32_16x16x64_i8 v[118:121], v[90:93], v[204:207], v[118:121]
	v_mfma_i32_16x16x64_i8 v[114:117], v[172:175], v[204:207], v[114:117]
	v_mfma_i32_16x16x64_i8 v[102:105], v[90:93], v[212:215], v[102:105]
	v_mfma_i32_16x16x64_i8 v[94:97], v[172:175], v[212:215], v[94:97]
	v_mfma_i32_16x16x64_i8 v[78:81], v[90:93], v[220:223], v[78:81]
	v_mfma_i32_16x16x64_i8 v[74:77], v[172:175], v[220:223], v[74:77]
	v_mfma_i32_16x16x64_i8 v[134:137], v[98:101], v[200:203], v[134:137]
	v_mfma_i32_16x16x64_i8 v[130:133], v[176:179], v[200:203], v[130:133]
	v_mfma_i32_16x16x64_i8 v[118:121], v[98:101], v[208:211], v[118:121]
	v_mfma_i32_16x16x64_i8 v[114:117], v[176:179], v[208:211], v[114:117]
	v_mfma_i32_16x16x64_i8 v[102:105], v[98:101], v[216:219], v[102:105]
	v_mfma_i32_16x16x64_i8 v[94:97], v[176:179], v[216:219], v[94:97]
	v_mfma_i32_16x16x64_i8 v[78:81], v[98:101], v[224:227], v[78:81]
	v_mfma_i32_16x16x64_i8 v[74:77], v[176:179], v[224:227], v[74:77]
	v_mfma_i32_16x16x64_i8 v[126:129], v[180:183], v[196:199], v[126:129]
	v_mfma_i32_16x16x64_i8 v[122:125], v[188:191], v[196:199], v[122:125]
	v_mfma_i32_16x16x64_i8 v[110:113], v[180:183], v[204:207], v[110:113]
	v_mfma_i32_16x16x64_i8 v[106:109], v[188:191], v[204:207], v[106:109]
	v_mfma_i32_16x16x64_i8 v[86:89], v[180:183], v[212:215], v[86:89]
	v_mfma_i32_16x16x64_i8 v[82:85], v[188:191], v[212:215], v[82:85]
	v_mfma_i32_16x16x64_i8 v[70:73], v[180:183], v[220:223], v[70:73]
	v_mfma_i32_16x16x64_i8 v[66:69], v[188:191], v[220:223], v[66:69]
	v_mfma_i32_16x16x64_i8 v[126:129], v[184:187], v[200:203], v[126:129]
	v_mfma_i32_16x16x64_i8 v[122:125], v[192:195], v[200:203], v[122:125]
	v_mfma_i32_16x16x64_i8 v[110:113], v[184:187], v[208:211], v[110:113]
	v_mfma_i32_16x16x64_i8 v[106:109], v[192:195], v[208:211], v[106:109]
	v_mfma_i32_16x16x64_i8 v[86:89], v[184:187], v[216:219], v[86:89]
	v_mfma_i32_16x16x64_i8 v[82:85], v[192:195], v[216:219], v[82:85]
	v_mfma_i32_16x16x64_i8 v[70:73], v[184:187], v[224:227], v[70:73]
	v_mfma_i32_16x16x64_i8 v[66:69], v[192:195], v[224:227], v[66:69]
	s_barrier
	s_add_i32 s54, s46, s33
	s_mov_b32 m0, s54
	ds_read_b128 v[196:199], v171 offset:16384
	ds_read_b128 v[200:203], v171 offset:17408
	ds_read_b128 v[204:207], v171 offset:18432
	ds_read_b128 v[208:211], v171 offset:19456
	ds_read_b128 v[212:215], v171 offset:20480
	ds_read_b128 v[216:219], v171 offset:21504
	ds_read_b128 v[220:223], v171 offset:22528
	ds_read_b128 v[224:227], v171 offset:23552
	global_load_lds_dwordx4 v142, s[24:25]
	s_add_i32 m0, s54, 0x2000
	s_add_u32 s54, s24, 0x4000
	s_addc_u32 s55, s25, 0
	s_add_i32 s56, s47, s33
	global_load_lds_dwordx4 v138, s[24:25]
	s_mov_b32 m0, s56
	s_nop 0
	global_load_lds_dwordx4 v142, s[54:55]
	s_add_i32 m0, s56, 0x2000
	s_nop 0
	global_load_lds_dwordx4 v138, s[54:55]
	s_waitcnt vmcnt(6)
	s_waitcnt lgkmcnt(0)
	s_barrier
	s_waitcnt lgkmcnt(0)
	v_mfma_i32_16x16x64_i8 v[62:65], v[90:93], v[196:199], v[62:65]
	v_mfma_i32_16x16x64_i8 v[58:61], v[172:175], v[196:199], v[58:61]
	v_mfma_i32_16x16x64_i8 v[46:49], v[90:93], v[204:207], v[46:49]
	v_mfma_i32_16x16x64_i8 v[42:45], v[172:175], v[204:207], v[42:45]
	v_mfma_i32_16x16x64_i8 v[30:33], v[90:93], v[212:215], v[30:33]
	v_mfma_i32_16x16x64_i8 v[26:29], v[172:175], v[212:215], v[26:29]
	v_mfma_i32_16x16x64_i8 v[14:17], v[90:93], v[220:223], v[14:17]
	v_mfma_i32_16x16x64_i8 v[10:13], v[172:175], v[220:223], v[10:13]
	v_mfma_i32_16x16x64_i8 v[62:65], v[98:101], v[200:203], v[62:65]
	v_mfma_i32_16x16x64_i8 v[58:61], v[176:179], v[200:203], v[58:61]
	v_mfma_i32_16x16x64_i8 v[46:49], v[98:101], v[208:211], v[46:49]
	v_mfma_i32_16x16x64_i8 v[42:45], v[176:179], v[208:211], v[42:45]
	v_mfma_i32_16x16x64_i8 v[30:33], v[98:101], v[216:219], v[30:33]
	v_mfma_i32_16x16x64_i8 v[26:29], v[176:179], v[216:219], v[26:29]
	v_mfma_i32_16x16x64_i8 v[14:17], v[98:101], v[224:227], v[14:17]
	v_mfma_i32_16x16x64_i8 v[10:13], v[176:179], v[224:227], v[10:13]
	v_mfma_i32_16x16x64_i8 v[54:57], v[180:183], v[196:199], v[54:57]
	v_mfma_i32_16x16x64_i8 v[50:53], v[188:191], v[196:199], v[50:53]
	v_mfma_i32_16x16x64_i8 v[38:41], v[180:183], v[204:207], v[38:41]
	v_mfma_i32_16x16x64_i8 v[34:37], v[188:191], v[204:207], v[34:37]
	v_mfma_i32_16x16x64_i8 v[22:25], v[180:183], v[212:215], v[22:25]
	v_mfma_i32_16x16x64_i8 v[18:21], v[188:191], v[212:215], v[18:21]
	v_mfma_i32_16x16x64_i8 v[6:9], v[180:183], v[220:223], v[6:9]
	v_mfma_i32_16x16x64_i8 v[2:5], v[188:191], v[220:223], v[2:5]
	v_mfma_i32_16x16x64_i8 v[54:57], v[184:187], v[200:203], v[54:57]
	v_mfma_i32_16x16x64_i8 v[50:53], v[192:195], v[200:203], v[50:53]
	v_mfma_i32_16x16x64_i8 v[38:41], v[184:187], v[208:211], v[38:41]
	v_mfma_i32_16x16x64_i8 v[34:37], v[192:195], v[208:211], v[34:37]
	v_mfma_i32_16x16x64_i8 v[22:25], v[184:187], v[216:219], v[22:25]
	v_mfma_i32_16x16x64_i8 v[18:21], v[192:195], v[216:219], v[18:21]
	v_mfma_i32_16x16x64_i8 v[6:9], v[184:187], v[224:227], v[6:9]
	v_mfma_i32_16x16x64_i8 v[2:5], v[192:195], v[224:227], v[2:5]
	s_barrier
; #define PG8_STAGE(bufoff, gbase, voff) do { _Pragma("unroll") for (int _i = 0; _i < 2; ++_i) \
;         __builtin_amdgcn_global_load_lds((const unsigned*)((const char*)(gbase) + (voff)[_i]), (LAS unsigned*)(lds + (bufoff) + ldsw + _i * 8192), 16, 0, 0); } while (0)
; #define PG8_LDA(dst, b, h) do { _Pragma("unroll") for (int m = 0; m < 4; ++m) _Pragma("unroll") for (int k = 0; k < 2; ++k) dst[m][k] = *(const LAS bf16x8*)(lds + PG8_SA(b, h) + aoff + m * 2048 + k * 1024); } while (0)
; #define PG8_LDB(dst, b, h) do { _Pragma("unroll") for (int n = 0; n < 2; ++n) _Pragma("unroll") for (int k = 0; k < 2; ++k) dst[n][k] = *(const LAS bf16x8*)(lds + PG8_SB(b, h) + boff + n * 2048 + k * 1024); } while (0)
; #define PG8_WAIT_V(n) asm volatile("s_waitcnt vmcnt(" #n ")" ::: "memory")
; #define PG8_WAIT_L(n) asm volatile("s_waitcnt lgkmcnt(" #n ")" ::: "memory")
; #define PG8_BAR __builtin_amdgcn_s_barrier()
; #define PG8_SCHED __builtin_amdgcn_sched_barrier(0)
; template <class Epi, class Sched, bool I8 = false>
; __device__ __forceinline__ void gemm_phase(LAS unsigned char* lds, const Gemm g, const Sched& S, const Epi& E) {
;     ...
;             PG8_LDB(B0, 1, 0); PG8_LDB(B1, 1, 1); PG8_SCHED; PG8_LDA(At, 1, 0); PG8_STAGE(PG8_SA(0, 1), a2 + hstepA, voffA);
;             PG8_WAIT_V(8); PG8_WAIT_L(0); PG8_BAR; PG8_MMA(0, 0, At, B0); PG8_MMA(0, 1, At, B1); PG8_BAR; PG8_SCHED;
;             PG8_LDA(At, 1, 1); PG8_STAGE(PG8_SB(1, 0), b3, voffB); PG8_STAGE(PG8_SB(1, 1), b3 + hstepB, voffB); PG8_STAGE(PG8_SA(1, 0), a3, voffA);
;             PG8_WAIT_V(8); PG8_WAIT_L(0); PG8_BAR; PG8_MMA(1, 0, At, B0); PG8_MMA(1, 1, At, B1); PG8_BAR; PG8_SCHED;
;         }
;         if (wr == 0) PG8_BAR;
	s_add_i32 s54, 0, 0x18000
	v_add_u32_e32 v146, s54, v165
	s_add_i32 s55, 0, 0x1c000
	ds_read_b128 v[90:93], v146
	ds_read_b128 v[98:101], v146 offset:1024
	ds_read_b128 v[172:175], v146 offset:2048
	ds_read_b128 v[176:179], v146 offset:3072
	v_add_u32_e32 v146, s55, v165
	ds_read_b128 v[180:183], v146
	ds_read_b128 v[184:187], v146 offset:1024
	ds_read_b128 v[188:191], v146 offset:2048
	ds_read_b128 v[192:195], v146 offset:3072
	s_mov_b32 m0, s36
	s_nop 0
	global_load_lds_dwordx4 v144, s[26:27]
	s_mov_b32 m0, s37
	s_nop 0
	global_load_lds_dwordx4 v140, s[26:27]
	s_add_u32 s26, s26, 0x4000
	s_addc_u32 s27, s27, 0
	s_mov_b32 m0, s38
	ds_read_b128 v[196:199], v171 offset:32768
	ds_read_b128 v[200:203], v171 offset:33792
	ds_read_b128 v[204:207], v171 offset:34816
	ds_read_b128 v[208:211], v171 offset:35840
	ds_read_b128 v[212:215], v171 offset:36864
	ds_read_b128 v[216:219], v171 offset:37888
	ds_read_b128 v[220:223], v171 offset:38912
	ds_read_b128 v[224:227], v171 offset:39936
	global_load_lds_dwordx4 v144, s[26:27]
	s_mov_b32 m0, s39
	s_nop 0
	global_load_lds_dwordx4 v140, s[26:27]
	s_waitcnt vmcnt(8)
	s_waitcnt lgkmcnt(0)
	s_barrier
	s_waitcnt lgkmcnt(0)
	v_mfma_i32_16x16x64_i8 v[134:137], v[90:93], v[196:199], v[134:137]
	v_mfma_i32_16x16x64_i8 v[130:133], v[172:175], v[196:199], v[130:133]
	v_mfma_i32_16x16x64_i8 v[118:121], v[90:93], v[204:207], v[118:121]
	v_mfma_i32_16x16x64_i8 v[114:117], v[172:175], v[204:207], v[114:117]
	v_mfma_i32_16x16x64_i8 v[102:105], v[90:93], v[212:215], v[102:105]
	v_mfma_i32_16x16x64_i8 v[94:97], v[172:175], v[212:215], v[94:97]
	v_mfma_i32_16x16x64_i8 v[78:81], v[90:93], v[220:223], v[78:81]
	v_mfma_i32_16x16x64_i8 v[74:77], v[172:175], v[220:223], v[74:77]
	v_mfma_i32_16x16x64_i8 v[134:137], v[98:101], v[200:203], v[134:137]
	v_mfma_i32_16x16x64_i8 v[130:133], v[176:179], v[200:203], v[130:133]
	v_mfma_i32_16x16x64_i8 v[118:121], v[98:101], v[208:211], v[118:121]
	v_mfma_i32_16x16x64_i8 v[114:117], v[176:179], v[208:211], v[114:117]
	v_mfma_i32_16x16x64_i8 v[102:105], v[98:101], v[216:219], v[102:105]
	v_mfma_i32_16x16x64_i8 v[94:97], v[176:179], v[216:219], v[94:97]
	v_mfma_i32_16x16x64_i8 v[78:81], v[98:101], v[224:227], v[78:81]
	v_mfma_i32_16x16x64_i8 v[74:77], v[176:179], v[224:227], v[74:77]
	v_mfma_i32_16x16x64_i8 v[126:129], v[180:183], v[196:199], v[126:129]
	v_mfma_i32_16x16x64_i8 v[122:125], v[188:191], v[196:199], v[122:125]
	v_mfma_i32_16x16x64_i8 v[110:113], v[180:183], v[204:207], v[110:113]
	v_mfma_i32_16x16x64_i8 v[106:109], v[188:191], v[204:207], v[106:109]
	v_mfma_i32_16x16x64_i8 v[86:89], v[180:183], v[212:215], v[86:89]
	v_mfma_i32_16x16x64_i8 v[82:85], v[188:191], v[212:215], v[82:85]
	v_mfma_i32_16x16x64_i8 v[70:73], v[180:183], v[220:223], v[70:73]
	v_mfma_i32_16x16x64_i8 v[66:69], v[188:191], v[220:223], v[66:69]
	v_mfma_i32_16x16x64_i8 v[126:129], v[184:187], v[200:203], v[126:129]
	v_mfma_i32_16x16x64_i8 v[122:125], v[192:195], v[200:203], v[122:125]
	v_mfma_i32_16x16x64_i8 v[110:113], v[184:187], v[208:211], v[110:113]
	v_mfma_i32_16x16x64_i8 v[106:109], v[192:195], v[208:211], v[106:109]
	v_mfma_i32_16x16x64_i8 v[86:89], v[184:187], v[216:219], v[86:89]
	v_mfma_i32_16x16x64_i8 v[82:85], v[192:195], v[216:219], v[82:85]
	v_mfma_i32_16x16x64_i8 v[70:73], v[184:187], v[224:227], v[70:73]
	v_mfma_i32_16x16x64_i8 v[66:69], v[192:195], v[224:227], v[66:69]
	s_barrier
	s_add_u32 s26, s24, 0x8000
	s_addc_u32 s27, s25, 0
	s_add_i32 s54, s54, s33
	s_mov_b32 m0, s54
	ds_read_b128 v[196:199], v171 offset:49152
	ds_read_b128 v[200:203], v171 offset:50176
	ds_read_b128 v[204:207], v171 offset:51200
	ds_read_b128 v[208:211], v171 offset:52224
	ds_read_b128 v[212:215], v171 offset:53248
	ds_read_b128 v[216:219], v171 offset:54272
	ds_read_b128 v[220:223], v171 offset:55296
	ds_read_b128 v[224:227], v171 offset:56320
	global_load_lds_dwordx4 v142, s[26:27]
	s_add_i32 m0, s54, 0x2000
	s_add_u32 s24, s24, 0xc000
	v_lshl_add_u64 v[158:159], s[26:27], 0, v[138:139]
	s_addc_u32 s25, s25, 0
	s_add_i32 s26, s55, s33
	global_load_lds_dwordx4 v[158:159], off
	s_mov_b32 m0, s26
	s_nop 0
	global_load_lds_dwordx4 v142, s[24:25]
	s_add_i32 m0, s26, 0x2000
	s_nop 0
	global_load_lds_dwordx4 v138, s[24:25]
	s_waitcnt vmcnt(6)
	s_waitcnt lgkmcnt(0)
	s_barrier
	s_waitcnt lgkmcnt(0)
	v_mfma_i32_16x16x64_i8 v[62:65], v[90:93], v[196:199], v[62:65]
	v_mfma_i32_16x16x64_i8 v[58:61], v[172:175], v[196:199], v[58:61]
	v_mfma_i32_16x16x64_i8 v[46:49], v[90:93], v[204:207], v[46:49]
	v_mfma_i32_16x16x64_i8 v[42:45], v[172:175], v[204:207], v[42:45]
	v_mfma_i32_16x16x64_i8 v[30:33], v[90:93], v[212:215], v[30:33]
	v_mfma_i32_16x16x64_i8 v[26:29], v[172:175], v[212:215], v[26:29]
	v_mfma_i32_16x16x64_i8 v[14:17], v[90:93], v[220:223], v[14:17]
	v_mfma_i32_16x16x64_i8 v[10:13], v[172:175], v[220:223], v[10:13]
	v_mfma_i32_16x16x64_i8 v[62:65], v[98:101], v[200:203], v[62:65]
	v_mfma_i32_16x16x64_i8 v[58:61], v[176:179], v[200:203], v[58:61]
	v_mfma_i32_16x16x64_i8 v[46:49], v[98:101], v[208:211], v[46:49]
	v_mfma_i32_16x16x64_i8 v[42:45], v[176:179], v[208:211], v[42:45]
	v_mfma_i32_16x16x64_i8 v[30:33], v[98:101], v[216:219], v[30:33]
	v_mfma_i32_16x16x64_i8 v[26:29], v[176:179], v[216:219], v[26:29]
	v_mfma_i32_16x16x64_i8 v[14:17], v[98:101], v[224:227], v[14:17]
	v_mfma_i32_16x16x64_i8 v[10:13], v[176:179], v[224:227], v[10:13]
	v_mfma_i32_16x16x64_i8 v[54:57], v[180:183], v[196:199], v[54:57]
	v_mfma_i32_16x16x64_i8 v[50:53], v[188:191], v[196:199], v[50:53]
	v_mfma_i32_16x16x64_i8 v[38:41], v[180:183], v[204:207], v[38:41]
	v_mfma_i32_16x16x64_i8 v[34:37], v[188:191], v[204:207], v[34:37]
	v_mfma_i32_16x16x64_i8 v[22:25], v[180:183], v[212:215], v[22:25]
	v_mfma_i32_16x16x64_i8 v[18:21], v[188:191], v[212:215], v[18:21]
	v_mfma_i32_16x16x64_i8 v[6:9], v[180:183], v[220:223], v[6:9]
	v_mfma_i32_16x16x64_i8 v[2:5], v[188:191], v[220:223], v[2:5]
	v_mfma_i32_16x16x64_i8 v[54:57], v[184:187], v[200:203], v[54:57]
	v_mfma_i32_16x16x64_i8 v[50:53], v[192:195], v[200:203], v[50:53]
	v_mfma_i32_16x16x64_i8 v[38:41], v[184:187], v[208:211], v[38:41]
	v_mfma_i32_16x16x64_i8 v[34:37], v[192:195], v[208:211], v[34:37]
	v_mfma_i32_16x16x64_i8 v[22:25], v[184:187], v[216:219], v[22:25]
	v_mfma_i32_16x16x64_i8 v[18:21], v[192:195], v[216:219], v[18:21]
	v_mfma_i32_16x16x64_i8 v[6:9], v[184:187], v[224:227], v[6:9]
	v_mfma_i32_16x16x64_i8 v[2:5], v[192:195], v[224:227], v[2:5]
	s_add_i32 s53, s53, 2
	s_add_u32 s20, s20, 0x10000
	s_addc_u32 s21, s21, 0
	s_add_u32 s51, s51, 0x10000
	s_addc_u32 s52, s52, 0
	s_cmp_gt_u32 s53, 29
	s_cbranch_scc1 .Lmy_last_0
	s_barrier
	s_branch .LBB0_1169
.Lmy_last_0:
	s_and_b64 vcc, exec, s[8:9]
	s_cbranch_vccz .LBB0_1172
	s_barrier

; #define PG8_STAGE(bufoff, gbase, voff) do { _Pragma("unroll") for (int _i = 0; _i < 2; ++_i) \
;         __builtin_amdgcn_global_load_lds((const unsigned*)((const char*)(gbase) + (voff)[_i]), (LAS unsigned*)(lds + (bufoff) + ldsw + _i * 8192), 16, 0, 0); } while (0)
; #define PG8_LDA(dst, b, h) do { _Pragma("unroll") for (int m = 0; m < 4; ++m) _Pragma("unroll") for (int k = 0; k < 2; ++k) dst[m][k] = *(const LAS bf16x8*)(lds + PG8_SA(b, h) + aoff + m * 2048 + k * 1024); } while (0)
; #define PG8_LDB(dst, b, h) do { _Pragma("unroll") for (int n = 0; n < 2; ++n) _Pragma("unroll") for (int k = 0; k < 2; ++k) dst[n][k] = *(const LAS bf16x8*)(lds + PG8_SB(b, h) + boff + n * 2048 + k * 1024); } while (0)
; #define PG8_WAIT_V(n) asm volatile("s_waitcnt vmcnt(" #n ")" ::: "memory")
; #define PG8_WAIT_L(n) asm volatile("s_waitcnt lgkmcnt(" #n ")" ::: "memory")
; #define PG8_BAR __builtin_amdgcn_s_barrier()
; #define PG8_SCHED __builtin_amdgcn_sched_barrier(0)
; template <class Epi, class Sched, bool I8 = false>
; __device__ __forceinline__ void gemm_phase(LAS unsigned char* lds, const Gemm g, const Sched& S, const Epi& E) {
;     ...
;             PG8_LDB(B0, 0, 0); PG8_LDB(B1, 0, 1); PG8_SCHED; PG8_LDA(At, 0, 0); PG8_STAGE(PG8_SA(1, 1), a1 + hstepA, voffA);
;             PG8_WAIT_V(8); PG8_WAIT_L(0); PG8_BAR; PG8_MMA(0, 0, At, B0); PG8_MMA(0, 1, At, B1); PG8_BAR; PG8_SCHED;
;             PG8_LDA(At, 0, 1); PG8_STAGE(PG8_SB(0, 0), b2, voffB); PG8_STAGE(PG8_SB(0, 1), b2 + hstepB, voffB); PG8_STAGE(PG8_SA(0, 0), a2, voffA);
;             PG8_WAIT_V(8); PG8_WAIT_L(0); PG8_BAR; PG8_MMA(1, 0, At, B0); PG8_MMA(1, 1, At, B1); PG8_BAR; PG8_SCHED;
.LBB0_1393:
	ds_read_b128 v[66:69], v180
	ds_read_b128 v[70:73], v180 offset:1024
	ds_read_b128 v[74:77], v180 offset:2048
	ds_read_b128 v[78:81], v180 offset:3072
	ds_read_b128 v[146:149], v181
	ds_read_b128 v[150:153], v181 offset:1024
	ds_read_b128 v[174:177], v181 offset:2048
	ds_read_b128 v[184:187], v181 offset:3072
	s_add_u32 s20, s18, 0x4000
	s_addc_u32 s21, s19, 0
	s_cmpk_eq_i32 s49, 0x52
	s_cselect_b32 s24, s0, s20
	s_cselect_b32 s25, s1, s21
	s_cselect_b32 s22, s16, s47
	s_cselect_b32 s23, s17, s48
	s_add_u32 s20, s24, 0x8000
	s_addc_u32 s21, s25, 0
	s_sub_u32 s98, s18, 0x4000
	s_subb_u32 s99, s19, 0
	s_mov_b32 m0, s37
	s_nop 0
	global_load_lds_dwordx4 v156, s[98:99]
	s_mov_b32 m0, s38
	s_nop 0
	global_load_lds_dwordx4 v160, s[98:99]
	s_add_i32 m0, s31, 0xc000
	ds_read_b128 v[188:191], v182
	ds_read_b128 v[192:195], v182 offset:1024
	ds_read_b128 v[196:199], v182 offset:2048
	ds_read_b128 v[200:203], v182 offset:3072
	ds_read_b128 v[204:207], v182 offset:4096
	ds_read_b128 v[208:211], v182 offset:5120
	ds_read_b128 v[212:215], v182 offset:6144
	ds_read_b128 v[216:219], v182 offset:7168
	global_load_lds_dwordx4 v166, s[18:19]
	s_add_i32 m0, s31, 0xe000
	s_nop 0
	global_load_lds_dwordx4 v168, s[18:19]
	s_waitcnt vmcnt(8)
	s_waitcnt lgkmcnt(0)
	s_barrier
	s_waitcnt lgkmcnt(0)
	v_mfma_i32_16x16x64_i8 v[142:145], v[66:69], v[188:191], v[142:145]
	v_mfma_i32_16x16x64_i8 v[138:141], v[74:77], v[188:191], v[138:141]
	v_mfma_i32_16x16x64_i8 v[126:129], v[66:69], v[196:199], v[126:129]
	v_mfma_i32_16x16x64_i8 v[122:125], v[74:77], v[196:199], v[122:125]
	v_mfma_i32_16x16x64_i8 v[110:113], v[66:69], v[204:207], v[110:113]
	v_mfma_i32_16x16x64_i8 v[106:109], v[74:77], v[204:207], v[106:109]
	v_mfma_i32_16x16x64_i8 v[94:97], v[66:69], v[212:215], v[94:97]
	v_mfma_i32_16x16x64_i8 v[90:93], v[74:77], v[212:215], v[90:93]
	v_mfma_i32_16x16x64_i8 v[142:145], v[70:73], v[192:195], v[142:145]
	v_mfma_i32_16x16x64_i8 v[138:141], v[78:81], v[192:195], v[138:141]
	v_mfma_i32_16x16x64_i8 v[126:129], v[70:73], v[200:203], v[126:129]
	v_mfma_i32_16x16x64_i8 v[122:125], v[78:81], v[200:203], v[122:125]
	v_mfma_i32_16x16x64_i8 v[110:113], v[70:73], v[208:211], v[110:113]
	v_mfma_i32_16x16x64_i8 v[106:109], v[78:81], v[208:211], v[106:109]
	v_mfma_i32_16x16x64_i8 v[94:97], v[70:73], v[216:219], v[94:97]
	v_mfma_i32_16x16x64_i8 v[90:93], v[78:81], v[216:219], v[90:93]
	v_mfma_i32_16x16x64_i8 v[134:137], v[146:149], v[188:191], v[134:137]
	v_mfma_i32_16x16x64_i8 v[130:133], v[174:177], v[188:191], v[130:133]
	v_mfma_i32_16x16x64_i8 v[118:121], v[146:149], v[196:199], v[118:121]
	v_mfma_i32_16x16x64_i8 v[114:117], v[174:177], v[196:199], v[114:117]
	v_mfma_i32_16x16x64_i8 v[102:105], v[146:149], v[204:207], v[102:105]
	v_mfma_i32_16x16x64_i8 v[98:101], v[174:177], v[204:207], v[98:101]
	v_mfma_i32_16x16x64_i8 v[86:89], v[146:149], v[212:215], v[86:89]
	v_mfma_i32_16x16x64_i8 v[82:85], v[174:177], v[212:215], v[82:85]
	v_mfma_i32_16x16x64_i8 v[134:137], v[150:153], v[192:195], v[134:137]
	v_mfma_i32_16x16x64_i8 v[130:133], v[184:187], v[192:195], v[130:133]
	v_mfma_i32_16x16x64_i8 v[118:121], v[150:153], v[200:203], v[118:121]
	v_mfma_i32_16x16x64_i8 v[114:117], v[184:187], v[200:203], v[114:117]
	v_mfma_i32_16x16x64_i8 v[102:105], v[150:153], v[208:211], v[102:105]
	v_mfma_i32_16x16x64_i8 v[98:101], v[184:187], v[208:211], v[98:101]
	v_mfma_i32_16x16x64_i8 v[86:89], v[150:153], v[216:219], v[86:89]
	v_mfma_i32_16x16x64_i8 v[82:85], v[184:187], v[216:219], v[82:85]
	s_barrier
	s_add_i32 s50, s41, s30
	s_mov_b32 m0, s50
	ds_read_b128 v[188:191], v182 offset:16384
	ds_read_b128 v[192:195], v182 offset:17408
	ds_read_b128 v[196:199], v182 offset:18432
	ds_read_b128 v[200:203], v182 offset:19456
	ds_read_b128 v[204:207], v182 offset:20480
	ds_read_b128 v[208:211], v182 offset:21504
	ds_read_b128 v[212:215], v182 offset:22528
	ds_read_b128 v[216:219], v182 offset:23552
	global_load_lds_dwordx4 v158, s[22:23]
	s_add_i32 m0, s50, 0x2000
	s_add_u32 s50, s22, 0x4000
	s_addc_u32 s51, s23, 0
	s_add_i32 s52, s42, s30
	global_load_lds_dwordx4 v162, s[22:23]
	s_mov_b32 m0, s52
	s_nop 0
	global_load_lds_dwordx4 v158, s[50:51]
	s_add_i32 m0, s52, 0x2000
	s_nop 0
	global_load_lds_dwordx4 v162, s[50:51]
	s_waitcnt vmcnt(6)
	s_waitcnt lgkmcnt(0)
	s_barrier
	s_waitcnt lgkmcnt(0)
	v_mfma_i32_16x16x64_i8 v[62:65], v[66:69], v[188:191], v[62:65]
	v_mfma_i32_16x16x64_i8 v[58:61], v[74:77], v[188:191], v[58:61]
	v_mfma_i32_16x16x64_i8 v[46:49], v[66:69], v[196:199], v[46:49]
	v_mfma_i32_16x16x64_i8 v[42:45], v[74:77], v[196:199], v[42:45]
	v_mfma_i32_16x16x64_i8 v[30:33], v[66:69], v[204:207], v[30:33]
	v_mfma_i32_16x16x64_i8 v[26:29], v[74:77], v[204:207], v[26:29]
	v_mfma_i32_16x16x64_i8 v[14:17], v[66:69], v[212:215], v[14:17]
	v_mfma_i32_16x16x64_i8 v[10:13], v[74:77], v[212:215], v[10:13]
	v_mfma_i32_16x16x64_i8 v[62:65], v[70:73], v[192:195], v[62:65]
	v_mfma_i32_16x16x64_i8 v[58:61], v[78:81], v[192:195], v[58:61]
	v_mfma_i32_16x16x64_i8 v[46:49], v[70:73], v[200:203], v[46:49]
	v_mfma_i32_16x16x64_i8 v[42:45], v[78:81], v[200:203], v[42:45]
	v_mfma_i32_16x16x64_i8 v[30:33], v[70:73], v[208:211], v[30:33]
	v_mfma_i32_16x16x64_i8 v[26:29], v[78:81], v[208:211], v[26:29]
	v_mfma_i32_16x16x64_i8 v[14:17], v[70:73], v[216:219], v[14:17]
	v_mfma_i32_16x16x64_i8 v[10:13], v[78:81], v[216:219], v[10:13]
	v_mfma_i32_16x16x64_i8 v[54:57], v[146:149], v[188:191], v[54:57]
	v_mfma_i32_16x16x64_i8 v[50:53], v[174:177], v[188:191], v[50:53]
	v_mfma_i32_16x16x64_i8 v[38:41], v[146:149], v[196:199], v[38:41]
	v_mfma_i32_16x16x64_i8 v[34:37], v[174:177], v[196:199], v[34:37]
	v_mfma_i32_16x16x64_i8 v[22:25], v[146:149], v[204:207], v[22:25]
	v_mfma_i32_16x16x64_i8 v[18:21], v[174:177], v[204:207], v[18:21]
	v_mfma_i32_16x16x64_i8 v[6:9], v[146:149], v[212:215], v[6:9]
	v_mfma_i32_16x16x64_i8 v[2:5], v[174:177], v[212:215], v[2:5]
	v_mfma_i32_16x16x64_i8 v[54:57], v[150:153], v[192:195], v[54:57]
	v_mfma_i32_16x16x64_i8 v[50:53], v[184:187], v[192:195], v[50:53]
	v_mfma_i32_16x16x64_i8 v[38:41], v[150:153], v[200:203], v[38:41]
	v_mfma_i32_16x16x64_i8 v[34:37], v[184:187], v[200:203], v[34:37]
	v_mfma_i32_16x16x64_i8 v[22:25], v[150:153], v[208:211], v[22:25]
	v_mfma_i32_16x16x64_i8 v[18:21], v[184:187], v[208:211], v[18:21]
	v_mfma_i32_16x16x64_i8 v[6:9], v[150:153], v[216:219], v[6:9]
	v_mfma_i32_16x16x64_i8 v[2:5], v[184:187], v[216:219], v[2:5]
	s_barrier
; #define PG8_STAGE(bufoff, gbase, voff) do { _Pragma("unroll") for (int _i = 0; _i < 2; ++_i) \
;         __builtin_amdgcn_global_load_lds((const unsigned*)((const char*)(gbase) + (voff)[_i]), (LAS unsigned*)(lds + (bufoff) + ldsw + _i * 8192), 16, 0, 0); } while (0)
; #define PG8_LDA(dst, b, h) do { _Pragma("unroll") for (int m = 0; m < 4; ++m) _Pragma("unroll") for (int k = 0; k < 2; ++k) dst[m][k] = *(const LAS bf16x8*)(lds + PG8_SA(b, h) + aoff + m * 2048 + k * 1024); } while (0)
; #define PG8_LDB(dst, b, h) do { _Pragma("unroll") for (int n = 0; n < 2; ++n) _Pragma("unroll") for (int k = 0; k < 2; ++k) dst[n][k] = *(const LAS bf16x8*)(lds + PG8_SB(b, h) + boff + n * 2048 + k * 1024); } while (0)
; #define PG8_WAIT_V(n) asm volatile("s_waitcnt vmcnt(" #n ")" ::: "memory")
; #define PG8_WAIT_L(n) asm volatile("s_waitcnt lgkmcnt(" #n ")" ::: "memory")
; #define PG8_BAR __builtin_amdgcn_s_barrier()
; #define PG8_SCHED __builtin_amdgcn_sched_barrier(0)
; template <class Epi, class Sched, bool I8 = false>
; __device__ __forceinline__ void gemm_phase(LAS unsigned char* lds, const Gemm g, const Sched& S, const Epi& E) {
;     ...
;             PG8_LDB(B0, 1, 0); PG8_LDB(B1, 1, 1); PG8_SCHED; PG8_LDA(At, 1, 0); PG8_STAGE(PG8_SA(0, 1), a2 + hstepA, voffA);
;             PG8_WAIT_V(8); PG8_WAIT_L(0); PG8_BAR; PG8_MMA(0, 0, At, B0); PG8_MMA(0, 1, At, B1); PG8_BAR; PG8_SCHED;
;             PG8_LDA(At, 1, 1); PG8_STAGE(PG8_SB(1, 0), b3, voffB); PG8_STAGE(PG8_SB(1, 1), b3 + hstepB, voffB); PG8_STAGE(PG8_SA(1, 0), a3, voffA);
;             PG8_WAIT_V(8); PG8_WAIT_L(0); PG8_BAR; PG8_MMA(1, 0, At, B0); PG8_MMA(1, 1, At, B1); PG8_BAR; PG8_SCHED;
;         }
	s_add_i32 s50, 0, 0x18000
	s_add_i32 s51, 0, 0x1c000
	v_add_u32_e32 v78, s50, v178
	v_add_u32_e32 v164, s51, v178
	ds_read_b128 v[66:69], v78
	ds_read_b128 v[70:73], v78 offset:1024
	ds_read_b128 v[74:77], v78 offset:2048
	ds_read_b128 v[78:81], v78 offset:3072
	ds_read_b128 v[146:149], v164
	ds_read_b128 v[150:153], v164 offset:1024
	ds_read_b128 v[174:177], v164 offset:2048
	ds_read_b128 v[184:187], v164 offset:3072
	s_mov_b32 m0, s31
	s_nop 0
	global_load_lds_dwordx4 v156, s[24:25]
	s_mov_b32 m0, s33
	s_nop 0
	global_load_lds_dwordx4 v160, s[24:25]
	s_add_u32 s24, s24, 0x4000
	s_addc_u32 s25, s25, 0
	s_mov_b32 m0, s34
	ds_read_b128 v[188:191], v182 offset:32768
	ds_read_b128 v[192:195], v182 offset:33792
	ds_read_b128 v[196:199], v182 offset:34816
	ds_read_b128 v[200:203], v182 offset:35840
	ds_read_b128 v[204:207], v182 offset:36864
	ds_read_b128 v[208:211], v182 offset:37888
	ds_read_b128 v[212:215], v182 offset:38912
	ds_read_b128 v[216:219], v182 offset:39936
	global_load_lds_dwordx4 v156, s[24:25]
	s_mov_b32 m0, s35
	s_nop 0
	global_load_lds_dwordx4 v160, s[24:25]
	s_waitcnt vmcnt(8)
	s_waitcnt lgkmcnt(0)
	s_barrier
	s_waitcnt lgkmcnt(0)
	v_mfma_i32_16x16x64_i8 v[142:145], v[66:69], v[188:191], v[142:145]
	v_mfma_i32_16x16x64_i8 v[138:141], v[74:77], v[188:191], v[138:141]
	v_mfma_i32_16x16x64_i8 v[126:129], v[66:69], v[196:199], v[126:129]
	v_mfma_i32_16x16x64_i8 v[122:125], v[74:77], v[196:199], v[122:125]
	v_mfma_i32_16x16x64_i8 v[110:113], v[66:69], v[204:207], v[110:113]
	v_mfma_i32_16x16x64_i8 v[106:109], v[74:77], v[204:207], v[106:109]
	v_mfma_i32_16x16x64_i8 v[94:97], v[66:69], v[212:215], v[94:97]
	v_mfma_i32_16x16x64_i8 v[90:93], v[74:77], v[212:215], v[90:93]
	v_mfma_i32_16x16x64_i8 v[142:145], v[70:73], v[192:195], v[142:145]
	v_mfma_i32_16x16x64_i8 v[138:141], v[78:81], v[192:195], v[138:141]
	v_mfma_i32_16x16x64_i8 v[126:129], v[70:73], v[200:203], v[126:129]
	v_mfma_i32_16x16x64_i8 v[122:125], v[78:81], v[200:203], v[122:125]
	v_mfma_i32_16x16x64_i8 v[110:113], v[70:73], v[208:211], v[110:113]
	v_mfma_i32_16x16x64_i8 v[106:109], v[78:81], v[208:211], v[106:109]
	v_mfma_i32_16x16x64_i8 v[94:97], v[70:73], v[216:219], v[94:97]
	v_mfma_i32_16x16x64_i8 v[90:93], v[78:81], v[216:219], v[90:93]
	v_mfma_i32_16x16x64_i8 v[134:137], v[146:149], v[188:191], v[134:137]
	v_mfma_i32_16x16x64_i8 v[130:133], v[174:177], v[188:191], v[130:133]
	v_mfma_i32_16x16x64_i8 v[118:121], v[146:149], v[196:199], v[118:121]
	v_mfma_i32_16x16x64_i8 v[114:117], v[174:177], v[196:199], v[114:117]
	v_mfma_i32_16x16x64_i8 v[102:105], v[146:149], v[204:207], v[102:105]
	v_mfma_i32_16x16x64_i8 v[98:101], v[174:177], v[204:207], v[98:101]
	v_mfma_i32_16x16x64_i8 v[86:89], v[146:149], v[212:215], v[86:89]
	v_mfma_i32_16x16x64_i8 v[82:85], v[174:177], v[212:215], v[82:85]
	v_mfma_i32_16x16x64_i8 v[134:137], v[150:153], v[192:195], v[134:137]
	v_mfma_i32_16x16x64_i8 v[130:133], v[184:187], v[192:195], v[130:133]
	v_mfma_i32_16x16x64_i8 v[118:121], v[150:153], v[200:203], v[118:121]
	v_mfma_i32_16x16x64_i8 v[114:117], v[184:187], v[200:203], v[114:117]
	v_mfma_i32_16x16x64_i8 v[102:105], v[150:153], v[208:211], v[102:105]
	v_mfma_i32_16x16x64_i8 v[98:101], v[184:187], v[208:211], v[98:101]
	v_mfma_i32_16x16x64_i8 v[86:89], v[150:153], v[216:219], v[86:89]
	v_mfma_i32_16x16x64_i8 v[82:85], v[184:187], v[216:219], v[82:85]
	s_barrier
	s_add_u32 s24, s22, 0x8000
	s_addc_u32 s25, s23, 0
	s_add_i32 s50, s50, s30
	s_mov_b32 m0, s50
	ds_read_b128 v[188:191], v182 offset:49152
	ds_read_b128 v[192:195], v182 offset:50176
	ds_read_b128 v[196:199], v182 offset:51200
	ds_read_b128 v[200:203], v182 offset:52224
	ds_read_b128 v[204:207], v182 offset:53248
	ds_read_b128 v[208:211], v182 offset:54272
	ds_read_b128 v[212:215], v182 offset:55296
	ds_read_b128 v[216:219], v182 offset:56320
	global_load_lds_dwordx4 v158, s[24:25]
	s_add_i32 m0, s50, 0x2000
	s_add_u32 s22, s22, 0xc000
	v_lshl_add_u64 v[220:221], s[24:25], 0, v[162:163]
	s_addc_u32 s23, s23, 0
	s_add_i32 s24, s51, s30
	global_load_lds_dwordx4 v[220:221], off
	s_mov_b32 m0, s24
	s_nop 0
	global_load_lds_dwordx4 v158, s[22:23]
	s_add_i32 m0, s24, 0x2000
	s_nop 0
	global_load_lds_dwordx4 v162, s[22:23]
	s_waitcnt vmcnt(6)
	s_waitcnt lgkmcnt(0)
	s_barrier
	s_waitcnt lgkmcnt(0)
	v_mfma_i32_16x16x64_i8 v[62:65], v[66:69], v[188:191], v[62:65]
	v_mfma_i32_16x16x64_i8 v[58:61], v[74:77], v[188:191], v[58:61]
	v_mfma_i32_16x16x64_i8 v[46:49], v[66:69], v[196:199], v[46:49]
	v_mfma_i32_16x16x64_i8 v[42:45], v[74:77], v[196:199], v[42:45]
	v_mfma_i32_16x16x64_i8 v[30:33], v[66:69], v[204:207], v[30:33]
	v_mfma_i32_16x16x64_i8 v[26:29], v[74:77], v[204:207], v[26:29]
	v_mfma_i32_16x16x64_i8 v[14:17], v[66:69], v[212:215], v[14:17]
	v_mfma_i32_16x16x64_i8 v[10:13], v[74:77], v[212:215], v[10:13]
	v_mfma_i32_16x16x64_i8 v[62:65], v[70:73], v[192:195], v[62:65]
	v_mfma_i32_16x16x64_i8 v[58:61], v[78:81], v[192:195], v[58:61]
	v_mfma_i32_16x16x64_i8 v[46:49], v[70:73], v[200:203], v[46:49]
	v_mfma_i32_16x16x64_i8 v[42:45], v[78:81], v[200:203], v[42:45]
	v_mfma_i32_16x16x64_i8 v[30:33], v[70:73], v[208:211], v[30:33]
	v_mfma_i32_16x16x64_i8 v[26:29], v[78:81], v[208:211], v[26:29]
	v_mfma_i32_16x16x64_i8 v[14:17], v[70:73], v[216:219], v[14:17]
	v_mfma_i32_16x16x64_i8 v[10:13], v[78:81], v[216:219], v[10:13]
	v_mfma_i32_16x16x64_i8 v[54:57], v[146:149], v[188:191], v[54:57]
	v_mfma_i32_16x16x64_i8 v[50:53], v[174:177], v[188:191], v[50:53]
	v_mfma_i32_16x16x64_i8 v[38:41], v[146:149], v[196:199], v[38:41]
	v_mfma_i32_16x16x64_i8 v[34:37], v[174:177], v[196:199], v[34:37]
	v_mfma_i32_16x16x64_i8 v[22:25], v[146:149], v[204:207], v[22:25]
	v_mfma_i32_16x16x64_i8 v[18:21], v[174:177], v[204:207], v[18:21]
	v_mfma_i32_16x16x64_i8 v[6:9], v[146:149], v[212:215], v[6:9]
	v_mfma_i32_16x16x64_i8 v[2:5], v[174:177], v[212:215], v[2:5]
	v_mfma_i32_16x16x64_i8 v[54:57], v[150:153], v[192:195], v[54:57]
	v_mfma_i32_16x16x64_i8 v[50:53], v[184:187], v[192:195], v[50:53]
	v_mfma_i32_16x16x64_i8 v[38:41], v[150:153], v[200:203], v[38:41]
	v_mfma_i32_16x16x64_i8 v[34:37], v[184:187], v[200:203], v[34:37]
	v_mfma_i32_16x16x64_i8 v[22:25], v[150:153], v[208:211], v[22:25]
	v_mfma_i32_16x16x64_i8 v[18:21], v[184:187], v[208:211], v[18:21]
	v_mfma_i32_16x16x64_i8 v[6:9], v[150:153], v[216:219], v[6:9]
	v_mfma_i32_16x16x64_i8 v[2:5], v[184:187], v[216:219], v[2:5]
	s_add_i32 s49, s49, 2
	s_add_u32 s18, s18, 0x10000
	s_addc_u32 s19, s19, 0
	s_add_u32 s47, s47, 0x10000
	s_addc_u32 s48, s48, 0
	s_cmpk_gt_u32 s49, 0x53
	s_cbranch_scc1 .Lmy_last_1
	s_barrier
	s_branch .LBB0_1393
.Lmy_last_1:
	s_and_b64 vcc, exec, s[14:15]
	s_cbranch_vccz .LBB0_1396
	s_barrier

; #define PG8_STAGE(bufoff, gbase, voff) do { _Pragma("unroll") for (int _i = 0; _i < 2; ++_i) \
;         __builtin_amdgcn_global_load_lds((const unsigned*)((const char*)(gbase) + (voff)[_i]), (LAS unsigned*)(lds + (bufoff) + ldsw + _i * 8192), 16, 0, 0); } while (0)
; #define PG8_LDA(dst, b, h) do { _Pragma("unroll") for (int m = 0; m < 4; ++m) _Pragma("unroll") for (int k = 0; k < 2; ++k) dst[m][k] = *(const LAS bf16x8*)(lds + PG8_SA(b, h) + aoff + m * 2048 + k * 1024); } while (0)
; #define PG8_LDB(dst, b, h) do { _Pragma("unroll") for (int n = 0; n < 2; ++n) _Pragma("unroll") for (int k = 0; k < 2; ++k) dst[n][k] = *(const LAS bf16x8*)(lds + PG8_SB(b, h) + boff + n * 2048 + k * 1024); } while (0)
; #define PG8_WAIT_V(n) asm volatile("s_waitcnt vmcnt(" #n ")" ::: "memory")
; #define PG8_WAIT_L(n) asm volatile("s_waitcnt lgkmcnt(" #n ")" ::: "memory")
; #define PG8_BAR __builtin_amdgcn_s_barrier()
; #define PG8_SCHED __builtin_amdgcn_sched_barrier(0)
; template <class Epi, class Sched, bool I8 = false>
; __device__ __forceinline__ void gemm_phase(LAS unsigned char* lds, const Gemm g, const Sched& S, const Epi& E) {
;     ...
;         for (int t = 0; t < nt; t += 2) {
;             const bool last = (t == nt - 2);
;             const char* a1 = cA + (size_t)(t + 1) * kstep;
;             const char* a2 = last ? nA : cA + (size_t)(t + 2) * kstep; const char* b2 = last ? nB : cB + (size_t)(t + 2) * kstep;
;             const char* a3 = a2 + kstep; const char* b3 = b2 + kstep;
;             PG8_LDB(B0, 0, 0); PG8_LDB(B1, 0, 1); PG8_SCHED; PG8_LDA(At, 0, 0); PG8_STAGE(PG8_SA(1, 1), a1 + hstepA, voffA);
;             PG8_WAIT_V(8); PG8_WAIT_L(0); PG8_BAR; PG8_MMA(0, 0, At, B0); PG8_MMA(0, 1, At, B1); PG8_BAR; PG8_SCHED;
;             PG8_LDA(At, 0, 1); PG8_STAGE(PG8_SB(0, 0), b2, voffB); PG8_STAGE(PG8_SB(0, 1), b2 + hstepB, voffB); PG8_STAGE(PG8_SA(0, 0), a2, voffA);
;             PG8_WAIT_V(8); PG8_WAIT_L(0); PG8_BAR; PG8_MMA(1, 0, At, B0); PG8_MMA(1, 1, At, B1); PG8_BAR; PG8_SCHED;
.LBB0_1482:
	ds_read_b128 v[152:155], v182
	ds_read_b128 v[156:159], v182 offset:1024
	ds_read_b128 v[160:163], v182 offset:2048
	ds_read_b128 v[164:167], v182 offset:3072
	ds_read_b128 v[168:171], v183
	ds_read_b128 v[172:175], v183 offset:1024
	ds_read_b128 v[176:179], v183 offset:2048
	ds_read_b128 v[186:189], v183 offset:3072
	s_add_u32 s38, s8, 0x4000
	s_addc_u32 s39, s9, 0
	s_cmp_eq_u32 s47, 60
	s_cselect_b32 s42, s31, s38
	s_cselect_b32 s43, s7, s39
	s_cselect_b32 s40, s44, s45
	s_cselect_b32 s41, s29, s46
	s_add_u32 s38, s42, 0x8000
	s_addc_u32 s39, s43, 0
	s_sub_u32 s98, s8, 0x4000
	s_subb_u32 s99, s9, 0
	s_mov_b32 m0, s58
	s_nop 0
	global_load_lds_dwordx4 v130, s[98:99]
	s_mov_b32 m0, s59
	s_nop 0
	global_load_lds_dwordx4 v134, s[98:99]
	s_add_i32 m0, s33, 0xc000
	ds_read_b128 v[190:193], v184
	ds_read_b128 v[194:197], v184 offset:1024
	ds_read_b128 v[198:201], v184 offset:2048
	ds_read_b128 v[202:205], v184 offset:3072
	ds_read_b128 v[206:209], v184 offset:4096
	ds_read_b128 v[210:213], v184 offset:5120
	ds_read_b128 v[214:217], v184 offset:6144
	ds_read_b128 v[218:221], v184 offset:7168
	global_load_lds_dwordx4 v144, s[8:9]
	s_add_i32 m0, s33, 0xe000
	s_nop 0
	global_load_lds_dwordx4 v146, s[8:9]
	s_waitcnt vmcnt(8)
	s_waitcnt lgkmcnt(0)
	s_barrier
	s_waitcnt lgkmcnt(0)
	v_mfma_f32_16x16x32_bf16 v[126:129], v[152:155], v[190:193], v[126:129]
	v_mfma_f32_16x16x32_bf16 v[122:125], v[160:163], v[190:193], v[122:125]
	v_mfma_f32_16x16x32_bf16 v[110:113], v[152:155], v[198:201], v[110:113]
	v_mfma_f32_16x16x32_bf16 v[106:109], v[160:163], v[198:201], v[106:109]
	v_mfma_f32_16x16x32_bf16 v[94:97], v[152:155], v[206:209], v[94:97]
	v_mfma_f32_16x16x32_bf16 v[90:93], v[160:163], v[206:209], v[90:93]
	v_mfma_f32_16x16x32_bf16 v[78:81], v[152:155], v[214:217], v[78:81]
	v_mfma_f32_16x16x32_bf16 v[74:77], v[160:163], v[214:217], v[74:77]
	v_mfma_f32_16x16x32_bf16 v[126:129], v[156:159], v[194:197], v[126:129]
	v_mfma_f32_16x16x32_bf16 v[122:125], v[164:167], v[194:197], v[122:125]
	v_mfma_f32_16x16x32_bf16 v[110:113], v[156:159], v[202:205], v[110:113]
	v_mfma_f32_16x16x32_bf16 v[106:109], v[164:167], v[202:205], v[106:109]
	v_mfma_f32_16x16x32_bf16 v[94:97], v[156:159], v[210:213], v[94:97]
	v_mfma_f32_16x16x32_bf16 v[90:93], v[164:167], v[210:213], v[90:93]
	v_mfma_f32_16x16x32_bf16 v[78:81], v[156:159], v[218:221], v[78:81]
	v_mfma_f32_16x16x32_bf16 v[74:77], v[164:167], v[218:221], v[74:77]
	v_mfma_f32_16x16x32_bf16 v[118:121], v[168:171], v[190:193], v[118:121]
	v_mfma_f32_16x16x32_bf16 v[114:117], v[176:179], v[190:193], v[114:117]
	v_mfma_f32_16x16x32_bf16 v[102:105], v[168:171], v[198:201], v[102:105]
	v_mfma_f32_16x16x32_bf16 v[98:101], v[176:179], v[198:201], v[98:101]
	v_mfma_f32_16x16x32_bf16 v[86:89], v[168:171], v[206:209], v[86:89]
	v_mfma_f32_16x16x32_bf16 v[82:85], v[176:179], v[206:209], v[82:85]
	v_mfma_f32_16x16x32_bf16 v[70:73], v[168:171], v[214:217], v[70:73]
	v_mfma_f32_16x16x32_bf16 v[66:69], v[176:179], v[214:217], v[66:69]
	v_mfma_f32_16x16x32_bf16 v[118:121], v[172:175], v[194:197], v[118:121]
	v_mfma_f32_16x16x32_bf16 v[114:117], v[186:189], v[194:197], v[114:117]
	v_mfma_f32_16x16x32_bf16 v[102:105], v[172:175], v[202:205], v[102:105]
	v_mfma_f32_16x16x32_bf16 v[98:101], v[186:189], v[202:205], v[98:101]
	v_mfma_f32_16x16x32_bf16 v[86:89], v[172:175], v[210:213], v[86:89]
	v_mfma_f32_16x16x32_bf16 v[82:85], v[186:189], v[210:213], v[82:85]
	v_mfma_f32_16x16x32_bf16 v[70:73], v[172:175], v[218:221], v[70:73]
	v_mfma_f32_16x16x32_bf16 v[66:69], v[186:189], v[218:221], v[66:69]
	s_barrier
	s_add_i32 s48, s63, s25
	s_mov_b32 m0, s48
	ds_read_b128 v[190:193], v184 offset:16384
	ds_read_b128 v[194:197], v184 offset:17408
	ds_read_b128 v[198:201], v184 offset:18432
	ds_read_b128 v[202:205], v184 offset:19456
	ds_read_b128 v[206:209], v184 offset:20480
	ds_read_b128 v[210:213], v184 offset:21504
	ds_read_b128 v[214:217], v184 offset:22528
	ds_read_b128 v[218:221], v184 offset:23552
	global_load_lds_dwordx4 v132, s[40:41]
	s_add_i32 m0, s48, 0x2000
	s_add_u32 s48, s40, 0x4000
	s_addc_u32 s49, s41, 0
	s_add_i32 s50, s64, s25
	global_load_lds_dwordx4 v136, s[40:41]
	s_mov_b32 m0, s50
	s_nop 0
	global_load_lds_dwordx4 v132, s[48:49]
	s_add_i32 m0, s50, 0x2000
	s_nop 0
	global_load_lds_dwordx4 v136, s[48:49]
	s_waitcnt vmcnt(6)
	s_waitcnt lgkmcnt(0)
	s_barrier
	s_waitcnt lgkmcnt(0)
	v_mfma_f32_16x16x32_bf16 v[62:65], v[152:155], v[190:193], v[62:65]
	v_mfma_f32_16x16x32_bf16 v[58:61], v[160:163], v[190:193], v[58:61]
	v_mfma_f32_16x16x32_bf16 v[46:49], v[152:155], v[198:201], v[46:49]
	v_mfma_f32_16x16x32_bf16 v[42:45], v[160:163], v[198:201], v[42:45]
	v_mfma_f32_16x16x32_bf16 v[30:33], v[152:155], v[206:209], v[30:33]
	v_mfma_f32_16x16x32_bf16 v[26:29], v[160:163], v[206:209], v[26:29]
	v_mfma_f32_16x16x32_bf16 v[14:17], v[152:155], v[214:217], v[14:17]
	v_mfma_f32_16x16x32_bf16 v[10:13], v[160:163], v[214:217], v[10:13]
	v_mfma_f32_16x16x32_bf16 v[62:65], v[156:159], v[194:197], v[62:65]
	v_mfma_f32_16x16x32_bf16 v[58:61], v[164:167], v[194:197], v[58:61]
	v_mfma_f32_16x16x32_bf16 v[46:49], v[156:159], v[202:205], v[46:49]
	v_mfma_f32_16x16x32_bf16 v[42:45], v[164:167], v[202:205], v[42:45]
	v_mfma_f32_16x16x32_bf16 v[30:33], v[156:159], v[210:213], v[30:33]
	v_mfma_f32_16x16x32_bf16 v[26:29], v[164:167], v[210:213], v[26:29]
	v_mfma_f32_16x16x32_bf16 v[14:17], v[156:159], v[218:221], v[14:17]
	v_mfma_f32_16x16x32_bf16 v[10:13], v[164:167], v[218:221], v[10:13]
	v_mfma_f32_16x16x32_bf16 v[54:57], v[168:171], v[190:193], v[54:57]
	v_mfma_f32_16x16x32_bf16 v[50:53], v[176:179], v[190:193], v[50:53]
	v_mfma_f32_16x16x32_bf16 v[38:41], v[168:171], v[198:201], v[38:41]
	v_mfma_f32_16x16x32_bf16 v[34:37], v[176:179], v[198:201], v[34:37]
	v_mfma_f32_16x16x32_bf16 v[22:25], v[168:171], v[206:209], v[22:25]
	v_mfma_f32_16x16x32_bf16 v[18:21], v[176:179], v[206:209], v[18:21]
	v_mfma_f32_16x16x32_bf16 v[6:9], v[168:171], v[214:217], v[6:9]
	v_mfma_f32_16x16x32_bf16 v[2:5], v[176:179], v[214:217], v[2:5]
	v_mfma_f32_16x16x32_bf16 v[54:57], v[172:175], v[194:197], v[54:57]
	v_mfma_f32_16x16x32_bf16 v[50:53], v[186:189], v[194:197], v[50:53]
	v_mfma_f32_16x16x32_bf16 v[38:41], v[172:175], v[202:205], v[38:41]
	v_mfma_f32_16x16x32_bf16 v[34:37], v[186:189], v[202:205], v[34:37]
	v_mfma_f32_16x16x32_bf16 v[22:25], v[172:175], v[210:213], v[22:25]
	v_mfma_f32_16x16x32_bf16 v[18:21], v[186:189], v[210:213], v[18:21]
	v_mfma_f32_16x16x32_bf16 v[6:9], v[172:175], v[218:221], v[6:9]
	v_mfma_f32_16x16x32_bf16 v[2:5], v[186:189], v[218:221], v[2:5]
	s_barrier
; #define PG8_STAGE(bufoff, gbase, voff) do { _Pragma("unroll") for (int _i = 0; _i < 2; ++_i) \
;         __builtin_amdgcn_global_load_lds((const unsigned*)((const char*)(gbase) + (voff)[_i]), (LAS unsigned*)(lds + (bufoff) + ldsw + _i * 8192), 16, 0, 0); } while (0)
; #define PG8_LDA(dst, b, h) do { _Pragma("unroll") for (int m = 0; m < 4; ++m) _Pragma("unroll") for (int k = 0; k < 2; ++k) dst[m][k] = *(const LAS bf16x8*)(lds + PG8_SA(b, h) + aoff + m * 2048 + k * 1024); } while (0)
; #define PG8_LDB(dst, b, h) do { _Pragma("unroll") for (int n = 0; n < 2; ++n) _Pragma("unroll") for (int k = 0; k < 2; ++k) dst[n][k] = *(const LAS bf16x8*)(lds + PG8_SB(b, h) + boff + n * 2048 + k * 1024); } while (0)
; #define PG8_WAIT_V(n) asm volatile("s_waitcnt vmcnt(" #n ")" ::: "memory")
; #define PG8_WAIT_L(n) asm volatile("s_waitcnt lgkmcnt(" #n ")" ::: "memory")
; #define PG8_BAR __builtin_amdgcn_s_barrier()
; #define PG8_SCHED __builtin_amdgcn_sched_barrier(0)
; template <class Epi, class Sched, bool I8 = false>
; __device__ __forceinline__ void gemm_phase(LAS unsigned char* lds, const Gemm g, const Sched& S, const Epi& E) {
;     ...
;             PG8_LDB(B0, 1, 0); PG8_LDB(B1, 1, 1); PG8_SCHED; PG8_LDA(At, 1, 0); PG8_STAGE(PG8_SA(0, 1), a2 + hstepA, voffA);
;             PG8_WAIT_V(8); PG8_WAIT_L(0); PG8_BAR; PG8_MMA(0, 0, At, B0); PG8_MMA(0, 1, At, B1); PG8_BAR; PG8_SCHED;
;             PG8_LDA(At, 1, 1); PG8_STAGE(PG8_SB(1, 0), b3, voffB); PG8_STAGE(PG8_SB(1, 1), b3 + hstepB, voffB); PG8_STAGE(PG8_SA(1, 0), a3, voffA);
;             PG8_WAIT_V(8); PG8_WAIT_L(0); PG8_BAR; PG8_MMA(1, 0, At, B0); PG8_MMA(1, 1, At, B1); PG8_BAR; PG8_SCHED;
;         }
	s_add_i32 s48, 0, 0x18000
	v_add_u32_e32 v138, s48, v181
	s_add_i32 s49, 0, 0x1c000
	ds_read_b128 v[152:155], v138
	ds_read_b128 v[156:159], v138 offset:1024
	ds_read_b128 v[160:163], v138 offset:2048
	ds_read_b128 v[164:167], v138 offset:3072
	v_add_u32_e32 v138, s49, v181
	ds_read_b128 v[168:171], v138
	ds_read_b128 v[172:175], v138 offset:1024
	ds_read_b128 v[176:179], v138 offset:2048
	ds_read_b128 v[186:189], v138 offset:3072
	s_mov_b32 m0, s33
	s_nop 0
	global_load_lds_dwordx4 v130, s[42:43]
	s_mov_b32 m0, s52
	s_nop 0
	global_load_lds_dwordx4 v134, s[42:43]
	s_add_u32 s42, s42, 0x4000
	s_addc_u32 s43, s43, 0
	s_mov_b32 m0, s53
	ds_read_b128 v[190:193], v184 offset:32768
	ds_read_b128 v[194:197], v184 offset:33792
	ds_read_b128 v[198:201], v184 offset:34816
	ds_read_b128 v[202:205], v184 offset:35840
	ds_read_b128 v[206:209], v184 offset:36864
	ds_read_b128 v[210:213], v184 offset:37888
	ds_read_b128 v[214:217], v184 offset:38912
	ds_read_b128 v[218:221], v184 offset:39936
	global_load_lds_dwordx4 v130, s[42:43]
	s_mov_b32 m0, s54
	s_nop 0
	global_load_lds_dwordx4 v134, s[42:43]
	s_waitcnt vmcnt(8)
	s_waitcnt lgkmcnt(0)
	s_barrier
	s_waitcnt lgkmcnt(0)
	v_mfma_f32_16x16x32_bf16 v[126:129], v[152:155], v[190:193], v[126:129]
	v_mfma_f32_16x16x32_bf16 v[122:125], v[160:163], v[190:193], v[122:125]
	v_mfma_f32_16x16x32_bf16 v[110:113], v[152:155], v[198:201], v[110:113]
	v_mfma_f32_16x16x32_bf16 v[106:109], v[160:163], v[198:201], v[106:109]
	v_mfma_f32_16x16x32_bf16 v[94:97], v[152:155], v[206:209], v[94:97]
	v_mfma_f32_16x16x32_bf16 v[90:93], v[160:163], v[206:209], v[90:93]
	v_mfma_f32_16x16x32_bf16 v[78:81], v[152:155], v[214:217], v[78:81]
	v_mfma_f32_16x16x32_bf16 v[74:77], v[160:163], v[214:217], v[74:77]
	v_mfma_f32_16x16x32_bf16 v[126:129], v[156:159], v[194:197], v[126:129]
	v_mfma_f32_16x16x32_bf16 v[122:125], v[164:167], v[194:197], v[122:125]
	v_mfma_f32_16x16x32_bf16 v[110:113], v[156:159], v[202:205], v[110:113]
	v_mfma_f32_16x16x32_bf16 v[106:109], v[164:167], v[202:205], v[106:109]
	v_mfma_f32_16x16x32_bf16 v[94:97], v[156:159], v[210:213], v[94:97]
	v_mfma_f32_16x16x32_bf16 v[90:93], v[164:167], v[210:213], v[90:93]
	v_mfma_f32_16x16x32_bf16 v[78:81], v[156:159], v[218:221], v[78:81]
	v_mfma_f32_16x16x32_bf16 v[74:77], v[164:167], v[218:221], v[74:77]
	v_mfma_f32_16x16x32_bf16 v[118:121], v[168:171], v[190:193], v[118:121]
	v_mfma_f32_16x16x32_bf16 v[114:117], v[176:179], v[190:193], v[114:117]
	v_mfma_f32_16x16x32_bf16 v[102:105], v[168:171], v[198:201], v[102:105]
	v_mfma_f32_16x16x32_bf16 v[98:101], v[176:179], v[198:201], v[98:101]
	v_mfma_f32_16x16x32_bf16 v[86:89], v[168:171], v[206:209], v[86:89]
	v_mfma_f32_16x16x32_bf16 v[82:85], v[176:179], v[206:209], v[82:85]
	v_mfma_f32_16x16x32_bf16 v[70:73], v[168:171], v[214:217], v[70:73]
	v_mfma_f32_16x16x32_bf16 v[66:69], v[176:179], v[214:217], v[66:69]
	v_mfma_f32_16x16x32_bf16 v[118:121], v[172:175], v[194:197], v[118:121]
	v_mfma_f32_16x16x32_bf16 v[114:117], v[186:189], v[194:197], v[114:117]
	v_mfma_f32_16x16x32_bf16 v[102:105], v[172:175], v[202:205], v[102:105]
	v_mfma_f32_16x16x32_bf16 v[98:101], v[186:189], v[202:205], v[98:101]
	v_mfma_f32_16x16x32_bf16 v[86:89], v[172:175], v[210:213], v[86:89]
	v_mfma_f32_16x16x32_bf16 v[82:85], v[186:189], v[210:213], v[82:85]
	v_mfma_f32_16x16x32_bf16 v[70:73], v[172:175], v[218:221], v[70:73]
	v_mfma_f32_16x16x32_bf16 v[66:69], v[186:189], v[218:221], v[66:69]
	s_barrier
	s_add_u32 s42, s40, 0x8000
	s_addc_u32 s43, s41, 0
	s_add_i32 s48, s48, s25
	s_mov_b32 m0, s48
	ds_read_b128 v[190:193], v184 offset:49152
	ds_read_b128 v[194:197], v184 offset:50176
	ds_read_b128 v[198:201], v184 offset:51200
	ds_read_b128 v[202:205], v184 offset:52224
	ds_read_b128 v[206:209], v184 offset:53248
	ds_read_b128 v[210:213], v184 offset:54272
	ds_read_b128 v[214:217], v184 offset:55296
	ds_read_b128 v[218:221], v184 offset:56320
	global_load_lds_dwordx4 v132, s[42:43]
	s_add_i32 m0, s48, 0x2000
	s_add_u32 s40, s40, 0xc000
	v_lshl_add_u64 v[222:223], s[42:43], 0, v[136:137]
	s_addc_u32 s41, s41, 0
	s_add_i32 s42, s49, s25
	global_load_lds_dwordx4 v[222:223], off
	s_mov_b32 m0, s42
	s_nop 0
	global_load_lds_dwordx4 v132, s[40:41]
	s_add_i32 m0, s42, 0x2000
	s_nop 0
	global_load_lds_dwordx4 v136, s[40:41]
	s_waitcnt vmcnt(6)
	s_waitcnt lgkmcnt(0)
	s_barrier
	s_waitcnt lgkmcnt(0)
	v_mfma_f32_16x16x32_bf16 v[62:65], v[152:155], v[190:193], v[62:65]
	v_mfma_f32_16x16x32_bf16 v[58:61], v[160:163], v[190:193], v[58:61]
	v_mfma_f32_16x16x32_bf16 v[46:49], v[152:155], v[198:201], v[46:49]
	v_mfma_f32_16x16x32_bf16 v[42:45], v[160:163], v[198:201], v[42:45]
	v_mfma_f32_16x16x32_bf16 v[30:33], v[152:155], v[206:209], v[30:33]
	v_mfma_f32_16x16x32_bf16 v[26:29], v[160:163], v[206:209], v[26:29]
	v_mfma_f32_16x16x32_bf16 v[14:17], v[152:155], v[214:217], v[14:17]
	v_mfma_f32_16x16x32_bf16 v[10:13], v[160:163], v[214:217], v[10:13]
	v_mfma_f32_16x16x32_bf16 v[62:65], v[156:159], v[194:197], v[62:65]
	v_mfma_f32_16x16x32_bf16 v[58:61], v[164:167], v[194:197], v[58:61]
	v_mfma_f32_16x16x32_bf16 v[46:49], v[156:159], v[202:205], v[46:49]
	v_mfma_f32_16x16x32_bf16 v[42:45], v[164:167], v[202:205], v[42:45]
	v_mfma_f32_16x16x32_bf16 v[30:33], v[156:159], v[210:213], v[30:33]
	v_mfma_f32_16x16x32_bf16 v[26:29], v[164:167], v[210:213], v[26:29]
	v_mfma_f32_16x16x32_bf16 v[14:17], v[156:159], v[218:221], v[14:17]
	v_mfma_f32_16x16x32_bf16 v[10:13], v[164:167], v[218:221], v[10:13]
	v_mfma_f32_16x16x32_bf16 v[54:57], v[168:171], v[190:193], v[54:57]
	v_mfma_f32_16x16x32_bf16 v[50:53], v[176:179], v[190:193], v[50:53]
	v_mfma_f32_16x16x32_bf16 v[38:41], v[168:171], v[198:201], v[38:41]
	v_mfma_f32_16x16x32_bf16 v[34:37], v[176:179], v[198:201], v[34:37]
	v_mfma_f32_16x16x32_bf16 v[22:25], v[168:171], v[206:209], v[22:25]
	v_mfma_f32_16x16x32_bf16 v[18:21], v[176:179], v[206:209], v[18:21]
	v_mfma_f32_16x16x32_bf16 v[6:9], v[168:171], v[214:217], v[6:9]
	v_mfma_f32_16x16x32_bf16 v[2:5], v[176:179], v[214:217], v[2:5]
	v_mfma_f32_16x16x32_bf16 v[54:57], v[172:175], v[194:197], v[54:57]
	v_mfma_f32_16x16x32_bf16 v[50:53], v[186:189], v[194:197], v[50:53]
	v_mfma_f32_16x16x32_bf16 v[38:41], v[172:175], v[202:205], v[38:41]
	v_mfma_f32_16x16x32_bf16 v[34:37], v[186:189], v[202:205], v[34:37]
	v_mfma_f32_16x16x32_bf16 v[22:25], v[172:175], v[210:213], v[22:25]
	v_mfma_f32_16x16x32_bf16 v[18:21], v[186:189], v[210:213], v[18:21]
	v_mfma_f32_16x16x32_bf16 v[6:9], v[172:175], v[218:221], v[6:9]
	v_mfma_f32_16x16x32_bf16 v[2:5], v[186:189], v[218:221], v[2:5]
	s_add_i32 s47, s47, 2
	s_add_u32 s8, s8, 0x10000
	s_addc_u32 s9, s9, 0
	s_add_u32 s45, s45, 0x10000
	s_addc_u32 s46, s46, 0
	s_cmp_gt_u32 s47, 61
	s_cbranch_scc1 .Lmy_last_2
	s_barrier
	s_branch .LBB0_1482
.Lmy_last_2:
	s_and_b64 vcc, exec, s[20:21]
	s_cbranch_vccz .LBB0_1485
	s_barrier

; #define PG8_STAGE(bufoff, gbase, voff) do { _Pragma("unroll") for (int _i = 0; _i < 2; ++_i) \
;         __builtin_amdgcn_global_load_lds((const unsigned*)((const char*)(gbase) + (voff)[_i]), (LAS unsigned*)(lds + (bufoff) + ldsw + _i * 8192), 16, 0, 0); } while (0)
; #define PG8_LDA(dst, b, h) do { _Pragma("unroll") for (int m = 0; m < 4; ++m) _Pragma("unroll") for (int k = 0; k < 2; ++k) dst[m][k] = *(const LAS bf16x8*)(lds + PG8_SA(b, h) + aoff + m * 2048 + k * 1024); } while (0)
; #define PG8_LDB(dst, b, h) do { _Pragma("unroll") for (int n = 0; n < 2; ++n) _Pragma("unroll") for (int k = 0; k < 2; ++k) dst[n][k] = *(const LAS bf16x8*)(lds + PG8_SB(b, h) + boff + n * 2048 + k * 1024); } while (0)
; #define PG8_WAIT_V(n) asm volatile("s_waitcnt vmcnt(" #n ")" ::: "memory")
; #define PG8_WAIT_L(n) asm volatile("s_waitcnt lgkmcnt(" #n ")" ::: "memory")
; #define PG8_BAR __builtin_amdgcn_s_barrier()
; #define PG8_SCHED __builtin_amdgcn_sched_barrier(0)
; template <class Epi, class Sched, bool I8 = false>
; __device__ __forceinline__ void gemm_phase(LAS unsigned char* lds, const Gemm g, const Sched& S, const Epi& E) {
;     ...
;         for (int t = 0; t < nt; t += 2) {
;             const bool last = (t == nt - 2);
;             const char* a1 = cA + (size_t)(t + 1) * kstep;
;             const char* a2 = last ? nA : cA + (size_t)(t + 2) * kstep; const char* b2 = last ? nB : cB + (size_t)(t + 2) * kstep;
;             const char* a3 = a2 + kstep; const char* b3 = b2 + kstep;
;             PG8_LDB(B0, 0, 0); PG8_LDB(B1, 0, 1); PG8_SCHED; PG8_LDA(At, 0, 0); PG8_STAGE(PG8_SA(1, 1), a1 + hstepA, voffA);
;             PG8_WAIT_V(8); PG8_WAIT_L(0); PG8_BAR; PG8_MMA(0, 0, At, B0); PG8_MMA(0, 1, At, B1); PG8_BAR; PG8_SCHED;
;             PG8_LDA(At, 0, 1); PG8_STAGE(PG8_SB(0, 0), b2, voffB); PG8_STAGE(PG8_SB(0, 1), b2 + hstepB, voffB); PG8_STAGE(PG8_SA(0, 0), a2, voffA);
;             PG8_WAIT_V(8); PG8_WAIT_L(0); PG8_BAR; PG8_MMA(1, 0, At, B0); PG8_MMA(1, 1, At, B1); PG8_BAR; PG8_SCHED;
.LBB0_2685:
	ds_read_b128 v[130:133], v166
	ds_read_b128 v[134:137], v166 offset:1024
	ds_read_b128 v[158:161], v166 offset:2048
	ds_read_b128 v[170:173], v166 offset:3072
	ds_read_b128 v[174:177], v167
	ds_read_b128 v[178:181], v167 offset:1024
	ds_read_b128 v[182:185], v167 offset:2048
	ds_read_b128 v[186:189], v167 offset:3072
	s_add_u32 s12, s10, 0x4000
	s_addc_u32 s13, s11, 0
	s_cmp_eq_u32 s45, 4
	s_cselect_b32 s16, s40, s12
	s_cselect_b32 s17, s39, s13
	s_cselect_b32 s14, s42, s43
	s_cselect_b32 s15, s41, s44
	s_add_u32 s12, s16, 0x8000
	s_addc_u32 s13, s17, 0
	s_sub_u32 s98, s10, 0x4000
	s_subb_u32 s99, s11, 0
	s_mov_b32 m0, s33
	s_nop 0
	global_load_lds_dwordx4 v144, s[98:99]
	s_mov_b32 m0, s34
	s_nop 0
	global_load_lds_dwordx4 v140, s[98:99]
	s_add_i32 m0, s26, 0xc000
	ds_read_b128 v[190:193], v168
	ds_read_b128 v[194:197], v168 offset:1024
	ds_read_b128 v[198:201], v168 offset:2048
	ds_read_b128 v[202:205], v168 offset:3072
	ds_read_b128 v[206:209], v168 offset:4096
	ds_read_b128 v[210:213], v168 offset:5120
	ds_read_b128 v[214:217], v168 offset:6144
	ds_read_b128 v[218:221], v168 offset:7168
	global_load_lds_dwordx4 v150, s[10:11]
	s_add_i32 m0, s26, 0xe000
	s_nop 0
	global_load_lds_dwordx4 v152, s[10:11]
	s_waitcnt vmcnt(8)
	s_waitcnt lgkmcnt(0)
	s_barrier
	s_waitcnt lgkmcnt(0)
	v_mfma_f32_16x16x32_bf16 v[126:129], v[130:133], v[190:193], v[126:129]
	v_mfma_f32_16x16x32_bf16 v[122:125], v[158:161], v[190:193], v[122:125]
	v_mfma_f32_16x16x32_bf16 v[118:121], v[130:133], v[198:201], v[118:121]
	v_mfma_f32_16x16x32_bf16 v[114:117], v[158:161], v[198:201], v[114:117]
	v_mfma_f32_16x16x32_bf16 v[110:113], v[130:133], v[206:209], v[110:113]
	v_mfma_f32_16x16x32_bf16 v[106:109], v[158:161], v[206:209], v[106:109]
	v_mfma_f32_16x16x32_bf16 v[102:105], v[130:133], v[214:217], v[102:105]
	v_mfma_f32_16x16x32_bf16 v[98:101], v[158:161], v[214:217], v[98:101]
	v_mfma_f32_16x16x32_bf16 v[126:129], v[134:137], v[194:197], v[126:129]
	v_mfma_f32_16x16x32_bf16 v[122:125], v[170:173], v[194:197], v[122:125]
	v_mfma_f32_16x16x32_bf16 v[118:121], v[134:137], v[202:205], v[118:121]
	v_mfma_f32_16x16x32_bf16 v[114:117], v[170:173], v[202:205], v[114:117]
	v_mfma_f32_16x16x32_bf16 v[110:113], v[134:137], v[210:213], v[110:113]
	v_mfma_f32_16x16x32_bf16 v[106:109], v[170:173], v[210:213], v[106:109]
	v_mfma_f32_16x16x32_bf16 v[102:105], v[134:137], v[218:221], v[102:105]
	v_mfma_f32_16x16x32_bf16 v[98:101], v[170:173], v[218:221], v[98:101]
	v_mfma_f32_16x16x32_bf16 v[62:65], v[174:177], v[190:193], v[62:65]
	v_mfma_f32_16x16x32_bf16 v[58:61], v[182:185], v[190:193], v[58:61]
	v_mfma_f32_16x16x32_bf16 v[54:57], v[174:177], v[198:201], v[54:57]
	v_mfma_f32_16x16x32_bf16 v[50:53], v[182:185], v[198:201], v[50:53]
	v_mfma_f32_16x16x32_bf16 v[46:49], v[174:177], v[206:209], v[46:49]
	v_mfma_f32_16x16x32_bf16 v[42:45], v[182:185], v[206:209], v[42:45]
	v_mfma_f32_16x16x32_bf16 v[38:41], v[174:177], v[214:217], v[38:41]
	v_mfma_f32_16x16x32_bf16 v[34:37], v[182:185], v[214:217], v[34:37]
	v_mfma_f32_16x16x32_bf16 v[62:65], v[178:181], v[194:197], v[62:65]
	v_mfma_f32_16x16x32_bf16 v[58:61], v[186:189], v[194:197], v[58:61]
	v_mfma_f32_16x16x32_bf16 v[54:57], v[178:181], v[202:205], v[54:57]
	v_mfma_f32_16x16x32_bf16 v[50:53], v[186:189], v[202:205], v[50:53]
	v_mfma_f32_16x16x32_bf16 v[46:49], v[178:181], v[210:213], v[46:49]
	v_mfma_f32_16x16x32_bf16 v[42:45], v[186:189], v[210:213], v[42:45]
	v_mfma_f32_16x16x32_bf16 v[38:41], v[178:181], v[218:221], v[38:41]
	v_mfma_f32_16x16x32_bf16 v[34:37], v[186:189], v[218:221], v[34:37]
	s_barrier
	s_add_i32 s46, s62, s22
	s_mov_b32 m0, s46
	ds_read_b128 v[190:193], v168 offset:16384
	ds_read_b128 v[194:197], v168 offset:17408
	ds_read_b128 v[198:201], v168 offset:18432
	ds_read_b128 v[202:205], v168 offset:19456
	ds_read_b128 v[206:209], v168 offset:20480
	ds_read_b128 v[210:213], v168 offset:21504
	ds_read_b128 v[214:217], v168 offset:22528
	ds_read_b128 v[218:221], v168 offset:23552
	global_load_lds_dwordx4 v142, s[14:15]
	s_add_i32 m0, s46, 0x2000
	s_add_u32 s46, s14, 0x4000
	s_addc_u32 s47, s15, 0
	s_add_i32 s48, s35, s22
	global_load_lds_dwordx4 v138, s[14:15]
	s_mov_b32 m0, s48
	s_nop 0
	global_load_lds_dwordx4 v142, s[46:47]
	s_add_i32 m0, s48, 0x2000
	s_nop 0
	global_load_lds_dwordx4 v138, s[46:47]
	s_waitcnt vmcnt(6)
	s_waitcnt lgkmcnt(0)
	s_barrier
	s_waitcnt lgkmcnt(0)
	v_mfma_f32_16x16x32_bf16 v[94:97], v[130:133], v[190:193], v[94:97]
	v_mfma_f32_16x16x32_bf16 v[90:93], v[158:161], v[190:193], v[90:93]
	v_mfma_f32_16x16x32_bf16 v[86:89], v[130:133], v[198:201], v[86:89]
	v_mfma_f32_16x16x32_bf16 v[82:85], v[158:161], v[198:201], v[82:85]
	v_mfma_f32_16x16x32_bf16 v[78:81], v[130:133], v[206:209], v[78:81]
	v_mfma_f32_16x16x32_bf16 v[74:77], v[158:161], v[206:209], v[74:77]
	v_mfma_f32_16x16x32_bf16 v[70:73], v[130:133], v[214:217], v[70:73]
	v_mfma_f32_16x16x32_bf16 v[66:69], v[158:161], v[214:217], v[66:69]
	v_mfma_f32_16x16x32_bf16 v[94:97], v[134:137], v[194:197], v[94:97]
	v_mfma_f32_16x16x32_bf16 v[90:93], v[170:173], v[194:197], v[90:93]
	v_mfma_f32_16x16x32_bf16 v[86:89], v[134:137], v[202:205], v[86:89]
	v_mfma_f32_16x16x32_bf16 v[82:85], v[170:173], v[202:205], v[82:85]
	v_mfma_f32_16x16x32_bf16 v[78:81], v[134:137], v[210:213], v[78:81]
	v_mfma_f32_16x16x32_bf16 v[74:77], v[170:173], v[210:213], v[74:77]
	v_mfma_f32_16x16x32_bf16 v[70:73], v[134:137], v[218:221], v[70:73]
	v_mfma_f32_16x16x32_bf16 v[66:69], v[170:173], v[218:221], v[66:69]
	v_mfma_f32_16x16x32_bf16 v[30:33], v[174:177], v[190:193], v[30:33]
	v_mfma_f32_16x16x32_bf16 v[26:29], v[182:185], v[190:193], v[26:29]
	v_mfma_f32_16x16x32_bf16 v[22:25], v[174:177], v[198:201], v[22:25]
	v_mfma_f32_16x16x32_bf16 v[18:21], v[182:185], v[198:201], v[18:21]
	v_mfma_f32_16x16x32_bf16 v[14:17], v[174:177], v[206:209], v[14:17]
	v_mfma_f32_16x16x32_bf16 v[10:13], v[182:185], v[206:209], v[10:13]
	v_mfma_f32_16x16x32_bf16 v[6:9], v[174:177], v[214:217], v[6:9]
	v_mfma_f32_16x16x32_bf16 v[2:5], v[182:185], v[214:217], v[2:5]
	v_mfma_f32_16x16x32_bf16 v[30:33], v[178:181], v[194:197], v[30:33]
	v_mfma_f32_16x16x32_bf16 v[26:29], v[186:189], v[194:197], v[26:29]
	v_mfma_f32_16x16x32_bf16 v[22:25], v[178:181], v[202:205], v[22:25]
	v_mfma_f32_16x16x32_bf16 v[18:21], v[186:189], v[202:205], v[18:21]
	v_mfma_f32_16x16x32_bf16 v[14:17], v[178:181], v[210:213], v[14:17]
	v_mfma_f32_16x16x32_bf16 v[10:13], v[186:189], v[210:213], v[10:13]
	v_mfma_f32_16x16x32_bf16 v[6:9], v[178:181], v[218:221], v[6:9]
	v_mfma_f32_16x16x32_bf16 v[2:5], v[186:189], v[218:221], v[2:5]
	s_barrier
; #define PG8_STAGE(bufoff, gbase, voff) do { _Pragma("unroll") for (int _i = 0; _i < 2; ++_i) \
;         __builtin_amdgcn_global_load_lds((const unsigned*)((const char*)(gbase) + (voff)[_i]), (LAS unsigned*)(lds + (bufoff) + ldsw + _i * 8192), 16, 0, 0); } while (0)
; #define PG8_LDA(dst, b, h) do { _Pragma("unroll") for (int m = 0; m < 4; ++m) _Pragma("unroll") for (int k = 0; k < 2; ++k) dst[m][k] = *(const LAS bf16x8*)(lds + PG8_SA(b, h) + aoff + m * 2048 + k * 1024); } while (0)
; #define PG8_LDB(dst, b, h) do { _Pragma("unroll") for (int n = 0; n < 2; ++n) _Pragma("unroll") for (int k = 0; k < 2; ++k) dst[n][k] = *(const LAS bf16x8*)(lds + PG8_SB(b, h) + boff + n * 2048 + k * 1024); } while (0)
; #define PG8_WAIT_V(n) asm volatile("s_waitcnt vmcnt(" #n ")" ::: "memory")
; #define PG8_WAIT_L(n) asm volatile("s_waitcnt lgkmcnt(" #n ")" ::: "memory")
; #define PG8_BAR __builtin_amdgcn_s_barrier()
; #define PG8_SCHED __builtin_amdgcn_sched_barrier(0)
; template <class Epi, class Sched, bool I8 = false>
; __device__ __forceinline__ void gemm_phase(LAS unsigned char* lds, const Gemm g, const Sched& S, const Epi& E) {
;     ...
;             PG8_LDB(B0, 1, 0); PG8_LDB(B1, 1, 1); PG8_SCHED; PG8_LDA(At, 1, 0); PG8_STAGE(PG8_SA(0, 1), a2 + hstepA, voffA);
;             PG8_WAIT_V(8); PG8_WAIT_L(0); PG8_BAR; PG8_MMA(0, 0, At, B0); PG8_MMA(0, 1, At, B1); PG8_BAR; PG8_SCHED;
;             PG8_LDA(At, 1, 1); PG8_STAGE(PG8_SB(1, 0), b3, voffB); PG8_STAGE(PG8_SB(1, 1), b3 + hstepB, voffB); PG8_STAGE(PG8_SA(1, 0), a3, voffA);
;             PG8_WAIT_V(8); PG8_WAIT_L(0); PG8_BAR; PG8_MMA(1, 0, At, B0); PG8_MMA(1, 1, At, B1); PG8_BAR; PG8_SCHED;
;         }
	s_add_i32 s46, 0, 0x18000
	v_add_u32_e32 v155, s46, v165
	s_add_i32 s47, 0, 0x1c000
	ds_read_b128 v[130:133], v155
	ds_read_b128 v[134:137], v155 offset:1024
	ds_read_b128 v[158:161], v155 offset:2048
	ds_read_b128 v[170:173], v155 offset:3072
	v_add_u32_e32 v155, s47, v165
	ds_read_b128 v[174:177], v155
	ds_read_b128 v[178:181], v155 offset:1024
	ds_read_b128 v[182:185], v155 offset:2048
	ds_read_b128 v[186:189], v155 offset:3072
	s_mov_b32 m0, s26
	s_nop 0
	global_load_lds_dwordx4 v144, s[16:17]
	s_mov_b32 m0, s27
	s_nop 0
	global_load_lds_dwordx4 v140, s[16:17]
	s_add_u32 s16, s16, 0x4000
	s_addc_u32 s17, s17, 0
	s_mov_b32 m0, s28
	ds_read_b128 v[190:193], v168 offset:32768
	ds_read_b128 v[194:197], v168 offset:33792
	ds_read_b128 v[198:201], v168 offset:34816
	ds_read_b128 v[202:205], v168 offset:35840
	ds_read_b128 v[206:209], v168 offset:36864
	ds_read_b128 v[210:213], v168 offset:37888
	ds_read_b128 v[214:217], v168 offset:38912
	ds_read_b128 v[218:221], v168 offset:39936
	global_load_lds_dwordx4 v144, s[16:17]
	s_mov_b32 m0, s29
	s_nop 0
	global_load_lds_dwordx4 v140, s[16:17]
	s_waitcnt vmcnt(8)
	s_waitcnt lgkmcnt(0)
	s_barrier
	s_waitcnt lgkmcnt(0)
	v_mfma_f32_16x16x32_bf16 v[126:129], v[130:133], v[190:193], v[126:129]
	v_mfma_f32_16x16x32_bf16 v[122:125], v[158:161], v[190:193], v[122:125]
	v_mfma_f32_16x16x32_bf16 v[118:121], v[130:133], v[198:201], v[118:121]
	v_mfma_f32_16x16x32_bf16 v[114:117], v[158:161], v[198:201], v[114:117]
	v_mfma_f32_16x16x32_bf16 v[110:113], v[130:133], v[206:209], v[110:113]
	v_mfma_f32_16x16x32_bf16 v[106:109], v[158:161], v[206:209], v[106:109]
	v_mfma_f32_16x16x32_bf16 v[102:105], v[130:133], v[214:217], v[102:105]
	v_mfma_f32_16x16x32_bf16 v[98:101], v[158:161], v[214:217], v[98:101]
	v_mfma_f32_16x16x32_bf16 v[126:129], v[134:137], v[194:197], v[126:129]
	v_mfma_f32_16x16x32_bf16 v[122:125], v[170:173], v[194:197], v[122:125]
	v_mfma_f32_16x16x32_bf16 v[118:121], v[134:137], v[202:205], v[118:121]
	v_mfma_f32_16x16x32_bf16 v[114:117], v[170:173], v[202:205], v[114:117]
	v_mfma_f32_16x16x32_bf16 v[110:113], v[134:137], v[210:213], v[110:113]
	v_mfma_f32_16x16x32_bf16 v[106:109], v[170:173], v[210:213], v[106:109]
	v_mfma_f32_16x16x32_bf16 v[102:105], v[134:137], v[218:221], v[102:105]
	v_mfma_f32_16x16x32_bf16 v[98:101], v[170:173], v[218:221], v[98:101]
	v_mfma_f32_16x16x32_bf16 v[62:65], v[174:177], v[190:193], v[62:65]
	v_mfma_f32_16x16x32_bf16 v[58:61], v[182:185], v[190:193], v[58:61]
	v_mfma_f32_16x16x32_bf16 v[54:57], v[174:177], v[198:201], v[54:57]
	v_mfma_f32_16x16x32_bf16 v[50:53], v[182:185], v[198:201], v[50:53]
	v_mfma_f32_16x16x32_bf16 v[46:49], v[174:177], v[206:209], v[46:49]
	v_mfma_f32_16x16x32_bf16 v[42:45], v[182:185], v[206:209], v[42:45]
	v_mfma_f32_16x16x32_bf16 v[38:41], v[174:177], v[214:217], v[38:41]
	v_mfma_f32_16x16x32_bf16 v[34:37], v[182:185], v[214:217], v[34:37]
	v_mfma_f32_16x16x32_bf16 v[62:65], v[178:181], v[194:197], v[62:65]
	v_mfma_f32_16x16x32_bf16 v[58:61], v[186:189], v[194:197], v[58:61]
	v_mfma_f32_16x16x32_bf16 v[54:57], v[178:181], v[202:205], v[54:57]
	v_mfma_f32_16x16x32_bf16 v[50:53], v[186:189], v[202:205], v[50:53]
	v_mfma_f32_16x16x32_bf16 v[46:49], v[178:181], v[210:213], v[46:49]
	v_mfma_f32_16x16x32_bf16 v[42:45], v[186:189], v[210:213], v[42:45]
	v_mfma_f32_16x16x32_bf16 v[38:41], v[178:181], v[218:221], v[38:41]
	v_mfma_f32_16x16x32_bf16 v[34:37], v[186:189], v[218:221], v[34:37]
	s_barrier
	s_add_u32 s16, s14, 0x8000
	s_addc_u32 s17, s15, 0
	s_add_i32 s46, s46, s22
	s_mov_b32 m0, s46
	ds_read_b128 v[190:193], v168 offset:49152
	ds_read_b128 v[194:197], v168 offset:50176
	ds_read_b128 v[198:201], v168 offset:51200
	ds_read_b128 v[202:205], v168 offset:52224
	ds_read_b128 v[206:209], v168 offset:53248
	ds_read_b128 v[210:213], v168 offset:54272
	ds_read_b128 v[214:217], v168 offset:55296
	ds_read_b128 v[218:221], v168 offset:56320
	global_load_lds_dwordx4 v142, s[16:17]
	s_add_i32 m0, s46, 0x2000
	s_add_u32 s14, s14, 0xc000
	v_lshl_add_u64 v[162:163], s[16:17], 0, v[138:139]
	s_addc_u32 s15, s15, 0
	s_add_i32 s16, s47, s22
	global_load_lds_dwordx4 v[162:163], off
	s_mov_b32 m0, s16
	s_nop 0
	global_load_lds_dwordx4 v142, s[14:15]
	s_add_i32 m0, s16, 0x2000
	s_nop 0
	global_load_lds_dwordx4 v138, s[14:15]
	s_waitcnt vmcnt(6)
	s_waitcnt lgkmcnt(0)
	s_barrier
	s_waitcnt lgkmcnt(0)
	v_mfma_f32_16x16x32_bf16 v[94:97], v[130:133], v[190:193], v[94:97]
	v_mfma_f32_16x16x32_bf16 v[90:93], v[158:161], v[190:193], v[90:93]
	v_mfma_f32_16x16x32_bf16 v[86:89], v[130:133], v[198:201], v[86:89]
	v_mfma_f32_16x16x32_bf16 v[82:85], v[158:161], v[198:201], v[82:85]
	v_mfma_f32_16x16x32_bf16 v[78:81], v[130:133], v[206:209], v[78:81]
	v_mfma_f32_16x16x32_bf16 v[74:77], v[158:161], v[206:209], v[74:77]
	v_mfma_f32_16x16x32_bf16 v[70:73], v[130:133], v[214:217], v[70:73]
	v_mfma_f32_16x16x32_bf16 v[66:69], v[158:161], v[214:217], v[66:69]
	v_mfma_f32_16x16x32_bf16 v[94:97], v[134:137], v[194:197], v[94:97]
	v_mfma_f32_16x16x32_bf16 v[90:93], v[170:173], v[194:197], v[90:93]
	v_mfma_f32_16x16x32_bf16 v[86:89], v[134:137], v[202:205], v[86:89]
	v_mfma_f32_16x16x32_bf16 v[82:85], v[170:173], v[202:205], v[82:85]
	v_mfma_f32_16x16x32_bf16 v[78:81], v[134:137], v[210:213], v[78:81]
	v_mfma_f32_16x16x32_bf16 v[74:77], v[170:173], v[210:213], v[74:77]
	v_mfma_f32_16x16x32_bf16 v[70:73], v[134:137], v[218:221], v[70:73]
	v_mfma_f32_16x16x32_bf16 v[66:69], v[170:173], v[218:221], v[66:69]
	v_mfma_f32_16x16x32_bf16 v[30:33], v[174:177], v[190:193], v[30:33]
	v_mfma_f32_16x16x32_bf16 v[26:29], v[182:185], v[190:193], v[26:29]
	v_mfma_f32_16x16x32_bf16 v[22:25], v[174:177], v[198:201], v[22:25]
	v_mfma_f32_16x16x32_bf16 v[18:21], v[182:185], v[198:201], v[18:21]
	v_mfma_f32_16x16x32_bf16 v[14:17], v[174:177], v[206:209], v[14:17]
	v_mfma_f32_16x16x32_bf16 v[10:13], v[182:185], v[206:209], v[10:13]
	v_mfma_f32_16x16x32_bf16 v[6:9], v[174:177], v[214:217], v[6:9]
	v_mfma_f32_16x16x32_bf16 v[2:5], v[182:185], v[214:217], v[2:5]
	v_mfma_f32_16x16x32_bf16 v[30:33], v[178:181], v[194:197], v[30:33]
	v_mfma_f32_16x16x32_bf16 v[26:29], v[186:189], v[194:197], v[26:29]
	v_mfma_f32_16x16x32_bf16 v[22:25], v[178:181], v[202:205], v[22:25]
	v_mfma_f32_16x16x32_bf16 v[18:21], v[186:189], v[202:205], v[18:21]
	v_mfma_f32_16x16x32_bf16 v[14:17], v[178:181], v[210:213], v[14:17]
	v_mfma_f32_16x16x32_bf16 v[10:13], v[186:189], v[210:213], v[10:13]
	v_mfma_f32_16x16x32_bf16 v[6:9], v[178:181], v[218:221], v[6:9]
	v_mfma_f32_16x16x32_bf16 v[2:5], v[186:189], v[218:221], v[2:5]
	s_add_i32 s45, s45, 2
	s_add_u32 s10, s10, 0x10000
	s_addc_u32 s11, s11, 0
	s_add_u32 s43, s43, 0x10000
	s_addc_u32 s44, s44, 0
	s_cmp_gt_u32 s45, 5
	s_cbranch_scc1 .Lmy_last_3
	s_barrier
	s_branch .LBB0_2685
.Lmy_last_3:
	s_and_b64 vcc, exec, s[6:7]
	s_cbranch_vccz .LBB0_2688
	s_barrier

; #define PG8_STAGE(bufoff, gbase, voff) do { _Pragma("unroll") for (int _i = 0; _i < 2; ++_i) \
;         __builtin_amdgcn_global_load_lds((const unsigned*)((const char*)(gbase) + (voff)[_i]), (LAS unsigned*)(lds + (bufoff) + ldsw + _i * 8192), 16, 0, 0); } while (0)
; #define PG8_LDA(dst, b, h) do { _Pragma("unroll") for (int m = 0; m < 4; ++m) _Pragma("unroll") for (int k = 0; k < 2; ++k) dst[m][k] = *(const LAS bf16x8*)(lds + PG8_SA(b, h) + aoff + m * 2048 + k * 1024); } while (0)
; #define PG8_LDB(dst, b, h) do { _Pragma("unroll") for (int n = 0; n < 2; ++n) _Pragma("unroll") for (int k = 0; k < 2; ++k) dst[n][k] = *(const LAS bf16x8*)(lds + PG8_SB(b, h) + boff + n * 2048 + k * 1024); } while (0)
; #define PG8_WAIT_V(n) asm volatile("s_waitcnt vmcnt(" #n ")" ::: "memory")
; #define PG8_WAIT_L(n) asm volatile("s_waitcnt lgkmcnt(" #n ")" ::: "memory")
; #define PG8_BAR __builtin_amdgcn_s_barrier()
; #define PG8_SCHED __builtin_amdgcn_sched_barrier(0)
; template <class Epi, class Sched, bool I8 = false>
; __device__ __forceinline__ void gemm_phase(LAS unsigned char* lds, const Gemm g, const Sched& S, const Epi& E) {
;     ...
;         for (int t = 0; t < nt; t += 2) {
;             const bool last = (t == nt - 2);
;             const char* a1 = cA + (size_t)(t + 1) * kstep;
;             const char* a2 = last ? nA : cA + (size_t)(t + 2) * kstep; const char* b2 = last ? nB : cB + (size_t)(t + 2) * kstep;
;             const char* a3 = a2 + kstep; const char* b3 = b2 + kstep;
;             PG8_LDB(B0, 0, 0); PG8_LDB(B1, 0, 1); PG8_SCHED; PG8_LDA(At, 0, 0); PG8_STAGE(PG8_SA(1, 1), a1 + hstepA, voffA);
;             PG8_WAIT_V(8); PG8_WAIT_L(0); PG8_BAR; PG8_MMA(0, 0, At, B0); PG8_MMA(0, 1, At, B1); PG8_BAR; PG8_SCHED;
;             PG8_LDA(At, 0, 1); PG8_STAGE(PG8_SB(0, 0), b2, voffB); PG8_STAGE(PG8_SB(0, 1), b2 + hstepB, voffB); PG8_STAGE(PG8_SA(0, 0), a2, voffA);
;             PG8_WAIT_V(8); PG8_WAIT_L(0); PG8_BAR; PG8_MMA(1, 0, At, B0); PG8_MMA(1, 1, At, B1); PG8_BAR; PG8_SCHED;
.LBB0_3744:
	ds_read_b128 v[130:133], v231
	ds_read_b128 v[134:137], v231 offset:1024
	ds_read_b128 v[138:141], v231 offset:2048
	ds_read_b128 v[142:145], v231 offset:3072
	ds_read_b128 v[146:149], v232
	ds_read_b128 v[150:153], v232 offset:1024
	ds_read_b128 v[154:157], v232 offset:2048
	ds_read_b128 v[158:161], v232 offset:3072
	s_add_u32 s34, s30, 0x4000
	s_addc_u32 s35, s31, 0
	s_cmp_eq_u32 s59, 60
	s_cselect_b32 s38, s23, s34
	s_cselect_b32 s39, s5, s35
	s_cselect_b32 s36, s29, s57
	s_cselect_b32 s37, s21, s58
	s_add_u32 s34, s38, 0x8000
	s_addc_u32 s35, s39, 0
	s_sub_u32 s98, s30, 0x4000
	s_subb_u32 s99, s31, 0
	s_mov_b32 m0, s51
	s_nop 0
	global_load_lds_dwordx4 v194, s[98:99]
	s_mov_b32 m0, s52
	s_nop 0
	global_load_lds_dwordx4 v198, s[98:99]
	s_add_i32 m0, s44, 0xc000
	ds_read_b128 v[162:165], v233
	ds_read_b128 v[166:169], v233 offset:1024
	ds_read_b128 v[170:173], v233 offset:2048
	ds_read_b128 v[174:177], v233 offset:3072
	ds_read_b128 v[178:181], v233 offset:4096
	ds_read_b128 v[182:185], v233 offset:5120
	ds_read_b128 v[186:189], v233 offset:6144
	ds_read_b128 v[190:193], v233 offset:7168
	global_load_lds_dwordx4 v204, s[30:31]
	s_add_i32 m0, s44, 0xe000
	s_nop 0
	global_load_lds_dwordx4 v206, s[30:31]
	s_waitcnt vmcnt(8)
	s_waitcnt lgkmcnt(0)
	s_barrier
	s_waitcnt lgkmcnt(0)
	v_mfma_f32_16x16x32_bf16 v[126:129], v[130:133], v[162:165], v[126:129]
	v_mfma_f32_16x16x32_bf16 v[122:125], v[138:141], v[162:165], v[122:125]
	v_mfma_f32_16x16x32_bf16 v[118:121], v[130:133], v[170:173], v[118:121]
	v_mfma_f32_16x16x32_bf16 v[110:113], v[138:141], v[170:173], v[110:113]
	v_mfma_f32_16x16x32_bf16 v[102:105], v[130:133], v[178:181], v[102:105]
	v_mfma_f32_16x16x32_bf16 v[94:97], v[138:141], v[178:181], v[94:97]
	v_mfma_f32_16x16x32_bf16 v[86:89], v[130:133], v[186:189], v[86:89]
	v_mfma_f32_16x16x32_bf16 v[78:81], v[138:141], v[186:189], v[78:81]
	v_mfma_f32_16x16x32_bf16 v[126:129], v[134:137], v[166:169], v[126:129]
	v_mfma_f32_16x16x32_bf16 v[122:125], v[142:145], v[166:169], v[122:125]
	v_mfma_f32_16x16x32_bf16 v[118:121], v[134:137], v[174:177], v[118:121]
	v_mfma_f32_16x16x32_bf16 v[110:113], v[142:145], v[174:177], v[110:113]
	v_mfma_f32_16x16x32_bf16 v[102:105], v[134:137], v[182:185], v[102:105]
	v_mfma_f32_16x16x32_bf16 v[94:97], v[142:145], v[182:185], v[94:97]
	v_mfma_f32_16x16x32_bf16 v[86:89], v[134:137], v[190:193], v[86:89]
	v_mfma_f32_16x16x32_bf16 v[78:81], v[142:145], v[190:193], v[78:81]
	v_mfma_f32_16x16x32_bf16 v[114:117], v[146:149], v[162:165], v[114:117]
	v_mfma_f32_16x16x32_bf16 v[106:109], v[154:157], v[162:165], v[106:109]
	v_mfma_f32_16x16x32_bf16 v[98:101], v[146:149], v[170:173], v[98:101]
	v_mfma_f32_16x16x32_bf16 v[90:93], v[154:157], v[170:173], v[90:93]
	v_mfma_f32_16x16x32_bf16 v[82:85], v[146:149], v[178:181], v[82:85]
	v_mfma_f32_16x16x32_bf16 v[74:77], v[154:157], v[178:181], v[74:77]
	v_mfma_f32_16x16x32_bf16 v[70:73], v[146:149], v[186:189], v[70:73]
	v_mfma_f32_16x16x32_bf16 v[66:69], v[154:157], v[186:189], v[66:69]
	v_mfma_f32_16x16x32_bf16 v[114:117], v[150:153], v[166:169], v[114:117]
	v_mfma_f32_16x16x32_bf16 v[106:109], v[158:161], v[166:169], v[106:109]
	v_mfma_f32_16x16x32_bf16 v[98:101], v[150:153], v[174:177], v[98:101]
	v_mfma_f32_16x16x32_bf16 v[90:93], v[158:161], v[174:177], v[90:93]
	v_mfma_f32_16x16x32_bf16 v[82:85], v[150:153], v[182:185], v[82:85]
	v_mfma_f32_16x16x32_bf16 v[74:77], v[158:161], v[182:185], v[74:77]
	v_mfma_f32_16x16x32_bf16 v[70:73], v[150:153], v[190:193], v[70:73]
	v_mfma_f32_16x16x32_bf16 v[66:69], v[158:161], v[190:193], v[66:69]
	s_barrier
	s_add_i32 s60, s55, s43
	s_mov_b32 m0, s60
	ds_read_b128 v[162:165], v233 offset:16384
	ds_read_b128 v[166:169], v233 offset:17408
	ds_read_b128 v[170:173], v233 offset:18432
	ds_read_b128 v[174:177], v233 offset:19456
	ds_read_b128 v[178:181], v233 offset:20480
	ds_read_b128 v[182:185], v233 offset:21504
	ds_read_b128 v[186:189], v233 offset:22528
	ds_read_b128 v[190:193], v233 offset:23552
	global_load_lds_dwordx4 v196, s[36:37]
	s_add_i32 m0, s60, 0x2000
	s_add_u32 s60, s36, 0x4000
	s_addc_u32 s61, s37, 0
	s_add_i32 s62, s56, s43
	global_load_lds_dwordx4 v200, s[36:37]
	s_mov_b32 m0, s62
	s_nop 0
	global_load_lds_dwordx4 v196, s[60:61]
	s_add_i32 m0, s62, 0x2000
	s_nop 0
	global_load_lds_dwordx4 v200, s[60:61]
	s_waitcnt vmcnt(6)
	s_waitcnt lgkmcnt(0)
	s_barrier
	s_waitcnt lgkmcnt(0)
	v_mfma_f32_16x16x32_bf16 v[62:65], v[130:133], v[162:165], v[62:65]
	v_mfma_f32_16x16x32_bf16 v[58:61], v[138:141], v[162:165], v[58:61]
	v_mfma_f32_16x16x32_bf16 v[54:57], v[130:133], v[170:173], v[54:57]
	v_mfma_f32_16x16x32_bf16 v[46:49], v[138:141], v[170:173], v[46:49]
	v_mfma_f32_16x16x32_bf16 v[38:41], v[130:133], v[178:181], v[38:41]
	v_mfma_f32_16x16x32_bf16 v[30:33], v[138:141], v[178:181], v[30:33]
	v_mfma_f32_16x16x32_bf16 v[22:25], v[130:133], v[186:189], v[22:25]
	v_mfma_f32_16x16x32_bf16 v[14:17], v[138:141], v[186:189], v[14:17]
	v_mfma_f32_16x16x32_bf16 v[62:65], v[134:137], v[166:169], v[62:65]
	v_mfma_f32_16x16x32_bf16 v[58:61], v[142:145], v[166:169], v[58:61]
	v_mfma_f32_16x16x32_bf16 v[54:57], v[134:137], v[174:177], v[54:57]
	v_mfma_f32_16x16x32_bf16 v[46:49], v[142:145], v[174:177], v[46:49]
	v_mfma_f32_16x16x32_bf16 v[38:41], v[134:137], v[182:185], v[38:41]
	v_mfma_f32_16x16x32_bf16 v[30:33], v[142:145], v[182:185], v[30:33]
	v_mfma_f32_16x16x32_bf16 v[22:25], v[134:137], v[190:193], v[22:25]
	v_mfma_f32_16x16x32_bf16 v[14:17], v[142:145], v[190:193], v[14:17]
	v_mfma_f32_16x16x32_bf16 v[50:53], v[146:149], v[162:165], v[50:53]
	v_mfma_f32_16x16x32_bf16 v[42:45], v[154:157], v[162:165], v[42:45]
	v_mfma_f32_16x16x32_bf16 v[34:37], v[146:149], v[170:173], v[34:37]
	v_mfma_f32_16x16x32_bf16 v[26:29], v[154:157], v[170:173], v[26:29]
	v_mfma_f32_16x16x32_bf16 v[18:21], v[146:149], v[178:181], v[18:21]
	v_mfma_f32_16x16x32_bf16 v[10:13], v[154:157], v[178:181], v[10:13]
	v_mfma_f32_16x16x32_bf16 v[6:9], v[146:149], v[186:189], v[6:9]
	v_mfma_f32_16x16x32_bf16 v[2:5], v[154:157], v[186:189], v[2:5]
	v_mfma_f32_16x16x32_bf16 v[50:53], v[150:153], v[166:169], v[50:53]
	v_mfma_f32_16x16x32_bf16 v[42:45], v[158:161], v[166:169], v[42:45]
	v_mfma_f32_16x16x32_bf16 v[34:37], v[150:153], v[174:177], v[34:37]
	v_mfma_f32_16x16x32_bf16 v[26:29], v[158:161], v[174:177], v[26:29]
	v_mfma_f32_16x16x32_bf16 v[18:21], v[150:153], v[182:185], v[18:21]
	v_mfma_f32_16x16x32_bf16 v[10:13], v[158:161], v[182:185], v[10:13]
	v_mfma_f32_16x16x32_bf16 v[6:9], v[150:153], v[190:193], v[6:9]
	v_mfma_f32_16x16x32_bf16 v[2:5], v[158:161], v[190:193], v[2:5]
	s_barrier
; #define PG8_STAGE(bufoff, gbase, voff) do { _Pragma("unroll") for (int _i = 0; _i < 2; ++_i) \
;         __builtin_amdgcn_global_load_lds((const unsigned*)((const char*)(gbase) + (voff)[_i]), (LAS unsigned*)(lds + (bufoff) + ldsw + _i * 8192), 16, 0, 0); } while (0)
; #define PG8_LDA(dst, b, h) do { _Pragma("unroll") for (int m = 0; m < 4; ++m) _Pragma("unroll") for (int k = 0; k < 2; ++k) dst[m][k] = *(const LAS bf16x8*)(lds + PG8_SA(b, h) + aoff + m * 2048 + k * 1024); } while (0)
; #define PG8_LDB(dst, b, h) do { _Pragma("unroll") for (int n = 0; n < 2; ++n) _Pragma("unroll") for (int k = 0; k < 2; ++k) dst[n][k] = *(const LAS bf16x8*)(lds + PG8_SB(b, h) + boff + n * 2048 + k * 1024); } while (0)
; #define PG8_WAIT_V(n) asm volatile("s_waitcnt vmcnt(" #n ")" ::: "memory")
; #define PG8_WAIT_L(n) asm volatile("s_waitcnt lgkmcnt(" #n ")" ::: "memory")
; #define PG8_BAR __builtin_amdgcn_s_barrier()
; #define PG8_SCHED __builtin_amdgcn_sched_barrier(0)
; template <class Epi, class Sched, bool I8 = false>
; __device__ __forceinline__ void gemm_phase(LAS unsigned char* lds, const Gemm g, const Sched& S, const Epi& E) {
;     ...
;             PG8_LDB(B0, 1, 0); PG8_LDB(B1, 1, 1); PG8_SCHED; PG8_LDA(At, 1, 0); PG8_STAGE(PG8_SA(0, 1), a2 + hstepA, voffA);
;             PG8_WAIT_V(8); PG8_WAIT_L(0); PG8_BAR; PG8_MMA(0, 0, At, B0); PG8_MMA(0, 1, At, B1); PG8_BAR; PG8_SCHED;
;             PG8_LDA(At, 1, 1); PG8_STAGE(PG8_SB(1, 0), b3, voffB); PG8_STAGE(PG8_SB(1, 1), b3 + hstepB, voffB); PG8_STAGE(PG8_SA(1, 0), a3, voffA);
;             PG8_WAIT_V(8); PG8_WAIT_L(0); PG8_BAR; PG8_MMA(1, 0, At, B0); PG8_MMA(1, 1, At, B1); PG8_BAR; PG8_SCHED;
;         }
	s_add_i32 s60, 0, 0x18000
	s_add_i32 s61, 0, 0x1c000
	v_add_u32_e32 v142, s60, v230
	v_add_u32_e32 v158, s61, v230
	ds_read_b128 v[130:133], v142
	ds_read_b128 v[134:137], v142 offset:1024
	ds_read_b128 v[138:141], v142 offset:2048
	ds_read_b128 v[142:145], v142 offset:3072
	ds_read_b128 v[146:149], v158
	ds_read_b128 v[150:153], v158 offset:1024
	ds_read_b128 v[154:157], v158 offset:2048
	ds_read_b128 v[158:161], v158 offset:3072
	s_mov_b32 m0, s44
	s_nop 0
	global_load_lds_dwordx4 v194, s[38:39]
	s_mov_b32 m0, s45
	s_nop 0
	global_load_lds_dwordx4 v198, s[38:39]
	s_add_u32 s38, s38, 0x4000
	s_addc_u32 s39, s39, 0
	s_mov_b32 m0, s46
	ds_read_b128 v[162:165], v233 offset:32768
	ds_read_b128 v[166:169], v233 offset:33792
	ds_read_b128 v[170:173], v233 offset:34816
	ds_read_b128 v[174:177], v233 offset:35840
	ds_read_b128 v[178:181], v233 offset:36864
	ds_read_b128 v[182:185], v233 offset:37888
	ds_read_b128 v[186:189], v233 offset:38912
	ds_read_b128 v[190:193], v233 offset:39936
	global_load_lds_dwordx4 v194, s[38:39]
	s_mov_b32 m0, s47
	s_nop 0
	global_load_lds_dwordx4 v198, s[38:39]
	s_waitcnt vmcnt(8)
	s_waitcnt lgkmcnt(0)
	s_barrier
	s_waitcnt lgkmcnt(0)
	v_mfma_f32_16x16x32_bf16 v[126:129], v[130:133], v[162:165], v[126:129]
	v_mfma_f32_16x16x32_bf16 v[122:125], v[138:141], v[162:165], v[122:125]
	v_mfma_f32_16x16x32_bf16 v[118:121], v[130:133], v[170:173], v[118:121]
	v_mfma_f32_16x16x32_bf16 v[110:113], v[138:141], v[170:173], v[110:113]
	v_mfma_f32_16x16x32_bf16 v[102:105], v[130:133], v[178:181], v[102:105]
	v_mfma_f32_16x16x32_bf16 v[94:97], v[138:141], v[178:181], v[94:97]
	v_mfma_f32_16x16x32_bf16 v[86:89], v[130:133], v[186:189], v[86:89]
	v_mfma_f32_16x16x32_bf16 v[78:81], v[138:141], v[186:189], v[78:81]
	v_mfma_f32_16x16x32_bf16 v[126:129], v[134:137], v[166:169], v[126:129]
	v_mfma_f32_16x16x32_bf16 v[122:125], v[142:145], v[166:169], v[122:125]
	v_mfma_f32_16x16x32_bf16 v[118:121], v[134:137], v[174:177], v[118:121]
	v_mfma_f32_16x16x32_bf16 v[110:113], v[142:145], v[174:177], v[110:113]
	v_mfma_f32_16x16x32_bf16 v[102:105], v[134:137], v[182:185], v[102:105]
	v_mfma_f32_16x16x32_bf16 v[94:97], v[142:145], v[182:185], v[94:97]
	v_mfma_f32_16x16x32_bf16 v[86:89], v[134:137], v[190:193], v[86:89]
	v_mfma_f32_16x16x32_bf16 v[78:81], v[142:145], v[190:193], v[78:81]
	v_mfma_f32_16x16x32_bf16 v[114:117], v[146:149], v[162:165], v[114:117]
	v_mfma_f32_16x16x32_bf16 v[106:109], v[154:157], v[162:165], v[106:109]
	v_mfma_f32_16x16x32_bf16 v[98:101], v[146:149], v[170:173], v[98:101]
	v_mfma_f32_16x16x32_bf16 v[90:93], v[154:157], v[170:173], v[90:93]
	v_mfma_f32_16x16x32_bf16 v[82:85], v[146:149], v[178:181], v[82:85]
	v_mfma_f32_16x16x32_bf16 v[74:77], v[154:157], v[178:181], v[74:77]
	v_mfma_f32_16x16x32_bf16 v[70:73], v[146:149], v[186:189], v[70:73]
	v_mfma_f32_16x16x32_bf16 v[66:69], v[154:157], v[186:189], v[66:69]
	v_mfma_f32_16x16x32_bf16 v[114:117], v[150:153], v[166:169], v[114:117]
	v_mfma_f32_16x16x32_bf16 v[106:109], v[158:161], v[166:169], v[106:109]
	v_mfma_f32_16x16x32_bf16 v[98:101], v[150:153], v[174:177], v[98:101]
	v_mfma_f32_16x16x32_bf16 v[90:93], v[158:161], v[174:177], v[90:93]
	v_mfma_f32_16x16x32_bf16 v[82:85], v[150:153], v[182:185], v[82:85]
	v_mfma_f32_16x16x32_bf16 v[74:77], v[158:161], v[182:185], v[74:77]
	v_mfma_f32_16x16x32_bf16 v[70:73], v[150:153], v[190:193], v[70:73]
	v_mfma_f32_16x16x32_bf16 v[66:69], v[158:161], v[190:193], v[66:69]
	s_barrier
	s_add_u32 s38, s36, 0x8000
	s_addc_u32 s39, s37, 0
	s_add_i32 s60, s60, s43
	s_mov_b32 m0, s60
	ds_read_b128 v[162:165], v233 offset:49152
	ds_read_b128 v[166:169], v233 offset:50176
	ds_read_b128 v[170:173], v233 offset:51200
	ds_read_b128 v[174:177], v233 offset:52224
	ds_read_b128 v[178:181], v233 offset:53248
	ds_read_b128 v[182:185], v233 offset:54272
	ds_read_b128 v[186:189], v233 offset:55296
	ds_read_b128 v[190:193], v233 offset:56320
	global_load_lds_dwordx4 v196, s[38:39]
	s_add_i32 m0, s60, 0x2000
	s_add_u32 s36, s36, 0xc000
	v_lshl_add_u64 v[212:213], s[38:39], 0, v[200:201]
	s_addc_u32 s37, s37, 0
	s_add_i32 s38, s61, s43
	global_load_lds_dwordx4 v[212:213], off
	s_mov_b32 m0, s38
	s_nop 0
	global_load_lds_dwordx4 v196, s[36:37]
	s_add_i32 m0, s38, 0x2000
	s_nop 0
	global_load_lds_dwordx4 v200, s[36:37]
	s_waitcnt vmcnt(6)
	s_waitcnt lgkmcnt(0)
	s_barrier
	s_waitcnt lgkmcnt(0)
	v_mfma_f32_16x16x32_bf16 v[62:65], v[130:133], v[162:165], v[62:65]
	v_mfma_f32_16x16x32_bf16 v[58:61], v[138:141], v[162:165], v[58:61]
	v_mfma_f32_16x16x32_bf16 v[54:57], v[130:133], v[170:173], v[54:57]
	v_mfma_f32_16x16x32_bf16 v[46:49], v[138:141], v[170:173], v[46:49]
	v_mfma_f32_16x16x32_bf16 v[38:41], v[130:133], v[178:181], v[38:41]
	v_mfma_f32_16x16x32_bf16 v[30:33], v[138:141], v[178:181], v[30:33]
	v_mfma_f32_16x16x32_bf16 v[22:25], v[130:133], v[186:189], v[22:25]
	v_mfma_f32_16x16x32_bf16 v[14:17], v[138:141], v[186:189], v[14:17]
	v_mfma_f32_16x16x32_bf16 v[62:65], v[134:137], v[166:169], v[62:65]
	v_mfma_f32_16x16x32_bf16 v[58:61], v[142:145], v[166:169], v[58:61]
	v_mfma_f32_16x16x32_bf16 v[54:57], v[134:137], v[174:177], v[54:57]
	v_mfma_f32_16x16x32_bf16 v[46:49], v[142:145], v[174:177], v[46:49]
	v_mfma_f32_16x16x32_bf16 v[38:41], v[134:137], v[182:185], v[38:41]
	v_mfma_f32_16x16x32_bf16 v[30:33], v[142:145], v[182:185], v[30:33]
	v_mfma_f32_16x16x32_bf16 v[22:25], v[134:137], v[190:193], v[22:25]
	v_mfma_f32_16x16x32_bf16 v[14:17], v[142:145], v[190:193], v[14:17]
	v_mfma_f32_16x16x32_bf16 v[50:53], v[146:149], v[162:165], v[50:53]
	v_mfma_f32_16x16x32_bf16 v[42:45], v[154:157], v[162:165], v[42:45]
	v_mfma_f32_16x16x32_bf16 v[34:37], v[146:149], v[170:173], v[34:37]
	v_mfma_f32_16x16x32_bf16 v[26:29], v[154:157], v[170:173], v[26:29]
	v_mfma_f32_16x16x32_bf16 v[18:21], v[146:149], v[178:181], v[18:21]
	v_mfma_f32_16x16x32_bf16 v[10:13], v[154:157], v[178:181], v[10:13]
	v_mfma_f32_16x16x32_bf16 v[6:9], v[146:149], v[186:189], v[6:9]
	v_mfma_f32_16x16x32_bf16 v[2:5], v[154:157], v[186:189], v[2:5]
	v_mfma_f32_16x16x32_bf16 v[50:53], v[150:153], v[166:169], v[50:53]
	v_mfma_f32_16x16x32_bf16 v[42:45], v[158:161], v[166:169], v[42:45]
	v_mfma_f32_16x16x32_bf16 v[34:37], v[150:153], v[174:177], v[34:37]
	v_mfma_f32_16x16x32_bf16 v[26:29], v[158:161], v[174:177], v[26:29]
	v_mfma_f32_16x16x32_bf16 v[18:21], v[150:153], v[182:185], v[18:21]
	v_mfma_f32_16x16x32_bf16 v[10:13], v[158:161], v[182:185], v[10:13]
	v_mfma_f32_16x16x32_bf16 v[6:9], v[150:153], v[190:193], v[6:9]
	v_mfma_f32_16x16x32_bf16 v[2:5], v[158:161], v[190:193], v[2:5]
	s_add_i32 s59, s59, 2
	s_add_u32 s30, s30, 0x10000
	s_addc_u32 s31, s31, 0
	s_add_u32 s57, s57, 0x10000
	s_addc_u32 s58, s58, 0
	s_cmp_gt_u32 s59, 61
	s_cbranch_scc1 .Lmy_last_4
	s_barrier
	s_branch .LBB0_3744

; #define PG8_STAGE(bufoff, gbase, voff) do { _Pragma("unroll") for (int _i = 0; _i < 2; ++_i) \
;         __builtin_amdgcn_global_load_lds((const unsigned*)((const char*)(gbase) + (voff)[_i]), (LAS unsigned*)(lds + (bufoff) + ldsw + _i * 8192), 16, 0, 0); } while (0)
; #define PG8_LDA(dst, b, h) do { _Pragma("unroll") for (int m = 0; m < 4; ++m) _Pragma("unroll") for (int k = 0; k < 2; ++k) dst[m][k] = *(const LAS bf16x8*)(lds + PG8_SA(b, h) + aoff + m * 2048 + k * 1024); } while (0)
; #define PG8_LDB(dst, b, h) do { _Pragma("unroll") for (int n = 0; n < 2; ++n) _Pragma("unroll") for (int k = 0; k < 2; ++k) dst[n][k] = *(const LAS bf16x8*)(lds + PG8_SB(b, h) + boff + n * 2048 + k * 1024); } while (0)
; #define PG8_WAIT_V(n) asm volatile("s_waitcnt vmcnt(" #n ")" ::: "memory")
; #define PG8_WAIT_L(n) asm volatile("s_waitcnt lgkmcnt(" #n ")" ::: "memory")
; #define PG8_BAR __builtin_amdgcn_s_barrier()
; #define PG8_SCHED __builtin_amdgcn_sched_barrier(0)
; template <class Epi, class Sched, bool I8 = false>
; __device__ __forceinline__ void gemm_phase(LAS unsigned char* lds, const Gemm g, const Sched& S, const Epi& E) {
;     ...
;         for (int t = 0; t < nt; t += 2) {
;             const bool last = (t == nt - 2);
;             const char* a1 = cA + (size_t)(t + 1) * kstep;
;             const char* a2 = last ? nA : cA + (size_t)(t + 2) * kstep; const char* b2 = last ? nB : cB + (size_t)(t + 2) * kstep;
;             const char* a3 = a2 + kstep; const char* b3 = b2 + kstep;
;             PG8_LDB(B0, 0, 0); PG8_LDB(B1, 0, 1); PG8_SCHED; PG8_LDA(At, 0, 0); PG8_STAGE(PG8_SA(1, 1), a1 + hstepA, voffA);
;             PG8_WAIT_V(8); PG8_WAIT_L(0); PG8_BAR; PG8_MMA(0, 0, At, B0); PG8_MMA(0, 1, At, B1); PG8_BAR; PG8_SCHED;
;             PG8_LDA(At, 0, 1); PG8_STAGE(PG8_SB(0, 0), b2, voffB); PG8_STAGE(PG8_SB(0, 1), b2 + hstepB, voffB); PG8_STAGE(PG8_SA(0, 0), a2, voffA);
;             PG8_WAIT_V(8); PG8_WAIT_L(0); PG8_BAR; PG8_MMA(1, 0, At, B0); PG8_MMA(1, 1, At, B1); PG8_BAR; PG8_SCHED;
.LBB0_4168:
	ds_read_b128 v[66:69], v178
	ds_read_b128 v[70:73], v178 offset:1024
	ds_read_b128 v[74:77], v178 offset:2048
	ds_read_b128 v[78:81], v178 offset:3072
	ds_read_b128 v[146:149], v179
	ds_read_b128 v[150:153], v179 offset:1024
	ds_read_b128 v[172:175], v179 offset:2048
	ds_read_b128 v[182:185], v179 offset:3072
	s_add_u32 s22, s20, 0x4000
	s_addc_u32 s23, s21, 0
	s_cmpk_eq_i32 s51, 0x52
	s_cselect_b32 s26, s0, s22
	s_cselect_b32 s27, s1, s23
	s_cselect_b32 s24, s18, s49
	s_cselect_b32 s25, s19, s50
	s_add_u32 s22, s26, 0x8000
	s_addc_u32 s23, s27, 0
	s_sub_u32 s98, s20, 0x4000
	s_subb_u32 s99, s21, 0
	s_mov_b32 m0, s39
	s_nop 0
	global_load_lds_dwordx4 v154, s[98:99]
	s_mov_b32 m0, s40
	s_nop 0
	global_load_lds_dwordx4 v158, s[98:99]
	s_add_i32 m0, s34, 0xc000
	ds_read_b128 v[186:189], v180
	ds_read_b128 v[190:193], v180 offset:1024
	ds_read_b128 v[194:197], v180 offset:2048
	ds_read_b128 v[198:201], v180 offset:3072
	ds_read_b128 v[202:205], v180 offset:4096
	ds_read_b128 v[206:209], v180 offset:5120
	ds_read_b128 v[210:213], v180 offset:6144
	ds_read_b128 v[214:217], v180 offset:7168
	global_load_lds_dwordx4 v164, s[20:21]
	s_add_i32 m0, s34, 0xe000
	s_nop 0
	global_load_lds_dwordx4 v166, s[20:21]
	s_waitcnt vmcnt(8)
	s_waitcnt lgkmcnt(0)
	s_barrier
	s_waitcnt lgkmcnt(0)
	v_mfma_i32_16x16x64_i8 v[142:145], v[66:69], v[186:189], v[142:145]
	v_mfma_i32_16x16x64_i8 v[138:141], v[74:77], v[186:189], v[138:141]
	v_mfma_i32_16x16x64_i8 v[126:129], v[66:69], v[194:197], v[126:129]
	v_mfma_i32_16x16x64_i8 v[122:125], v[74:77], v[194:197], v[122:125]
	v_mfma_i32_16x16x64_i8 v[110:113], v[66:69], v[202:205], v[110:113]
	v_mfma_i32_16x16x64_i8 v[106:109], v[74:77], v[202:205], v[106:109]
	v_mfma_i32_16x16x64_i8 v[94:97], v[66:69], v[210:213], v[94:97]
	v_mfma_i32_16x16x64_i8 v[90:93], v[74:77], v[210:213], v[90:93]
	v_mfma_i32_16x16x64_i8 v[142:145], v[70:73], v[190:193], v[142:145]
	v_mfma_i32_16x16x64_i8 v[138:141], v[78:81], v[190:193], v[138:141]
	v_mfma_i32_16x16x64_i8 v[126:129], v[70:73], v[198:201], v[126:129]
	v_mfma_i32_16x16x64_i8 v[122:125], v[78:81], v[198:201], v[122:125]
	v_mfma_i32_16x16x64_i8 v[110:113], v[70:73], v[206:209], v[110:113]
	v_mfma_i32_16x16x64_i8 v[106:109], v[78:81], v[206:209], v[106:109]
	v_mfma_i32_16x16x64_i8 v[94:97], v[70:73], v[214:217], v[94:97]
	v_mfma_i32_16x16x64_i8 v[90:93], v[78:81], v[214:217], v[90:93]
	v_mfma_i32_16x16x64_i8 v[134:137], v[146:149], v[186:189], v[134:137]
	v_mfma_i32_16x16x64_i8 v[130:133], v[172:175], v[186:189], v[130:133]
	v_mfma_i32_16x16x64_i8 v[118:121], v[146:149], v[194:197], v[118:121]
	v_mfma_i32_16x16x64_i8 v[114:117], v[172:175], v[194:197], v[114:117]
	v_mfma_i32_16x16x64_i8 v[102:105], v[146:149], v[202:205], v[102:105]
	v_mfma_i32_16x16x64_i8 v[98:101], v[172:175], v[202:205], v[98:101]
	v_mfma_i32_16x16x64_i8 v[86:89], v[146:149], v[210:213], v[86:89]
	v_mfma_i32_16x16x64_i8 v[82:85], v[172:175], v[210:213], v[82:85]
	v_mfma_i32_16x16x64_i8 v[134:137], v[150:153], v[190:193], v[134:137]
	v_mfma_i32_16x16x64_i8 v[130:133], v[182:185], v[190:193], v[130:133]
	v_mfma_i32_16x16x64_i8 v[118:121], v[150:153], v[198:201], v[118:121]
	v_mfma_i32_16x16x64_i8 v[114:117], v[182:185], v[198:201], v[114:117]
	v_mfma_i32_16x16x64_i8 v[102:105], v[150:153], v[206:209], v[102:105]
	v_mfma_i32_16x16x64_i8 v[98:101], v[182:185], v[206:209], v[98:101]
	v_mfma_i32_16x16x64_i8 v[86:89], v[150:153], v[214:217], v[86:89]
	v_mfma_i32_16x16x64_i8 v[82:85], v[182:185], v[214:217], v[82:85]
	s_barrier
	s_add_i32 s52, s43, s33
	s_mov_b32 m0, s52
	ds_read_b128 v[186:189], v180 offset:16384
	ds_read_b128 v[190:193], v180 offset:17408
	ds_read_b128 v[194:197], v180 offset:18432
	ds_read_b128 v[198:201], v180 offset:19456
	ds_read_b128 v[202:205], v180 offset:20480
	ds_read_b128 v[206:209], v180 offset:21504
	ds_read_b128 v[210:213], v180 offset:22528
	ds_read_b128 v[214:217], v180 offset:23552
	global_load_lds_dwordx4 v156, s[24:25]
	s_add_i32 m0, s52, 0x2000
	s_add_u32 s52, s24, 0x4000
	s_addc_u32 s53, s25, 0
	s_add_i32 s54, s44, s33
	global_load_lds_dwordx4 v160, s[24:25]
	s_mov_b32 m0, s54
	s_nop 0
	global_load_lds_dwordx4 v156, s[52:53]
	s_add_i32 m0, s54, 0x2000
	s_nop 0
	global_load_lds_dwordx4 v160, s[52:53]
	s_waitcnt vmcnt(6)
	s_waitcnt lgkmcnt(0)
	s_barrier
	s_waitcnt lgkmcnt(0)
	v_mfma_i32_16x16x64_i8 v[62:65], v[66:69], v[186:189], v[62:65]
	v_mfma_i32_16x16x64_i8 v[58:61], v[74:77], v[186:189], v[58:61]
	v_mfma_i32_16x16x64_i8 v[46:49], v[66:69], v[194:197], v[46:49]
	v_mfma_i32_16x16x64_i8 v[42:45], v[74:77], v[194:197], v[42:45]
	v_mfma_i32_16x16x64_i8 v[30:33], v[66:69], v[202:205], v[30:33]
	v_mfma_i32_16x16x64_i8 v[26:29], v[74:77], v[202:205], v[26:29]
	v_mfma_i32_16x16x64_i8 v[14:17], v[66:69], v[210:213], v[14:17]
	v_mfma_i32_16x16x64_i8 v[10:13], v[74:77], v[210:213], v[10:13]
	v_mfma_i32_16x16x64_i8 v[62:65], v[70:73], v[190:193], v[62:65]
	v_mfma_i32_16x16x64_i8 v[58:61], v[78:81], v[190:193], v[58:61]
	v_mfma_i32_16x16x64_i8 v[46:49], v[70:73], v[198:201], v[46:49]
	v_mfma_i32_16x16x64_i8 v[42:45], v[78:81], v[198:201], v[42:45]
	v_mfma_i32_16x16x64_i8 v[30:33], v[70:73], v[206:209], v[30:33]
	v_mfma_i32_16x16x64_i8 v[26:29], v[78:81], v[206:209], v[26:29]
	v_mfma_i32_16x16x64_i8 v[14:17], v[70:73], v[214:217], v[14:17]
	v_mfma_i32_16x16x64_i8 v[10:13], v[78:81], v[214:217], v[10:13]
	v_mfma_i32_16x16x64_i8 v[54:57], v[146:149], v[186:189], v[54:57]
	v_mfma_i32_16x16x64_i8 v[50:53], v[172:175], v[186:189], v[50:53]
	v_mfma_i32_16x16x64_i8 v[38:41], v[146:149], v[194:197], v[38:41]
	v_mfma_i32_16x16x64_i8 v[34:37], v[172:175], v[194:197], v[34:37]
	v_mfma_i32_16x16x64_i8 v[22:25], v[146:149], v[202:205], v[22:25]
	v_mfma_i32_16x16x64_i8 v[18:21], v[172:175], v[202:205], v[18:21]
	v_mfma_i32_16x16x64_i8 v[6:9], v[146:149], v[210:213], v[6:9]
	v_mfma_i32_16x16x64_i8 v[2:5], v[172:175], v[210:213], v[2:5]
	v_mfma_i32_16x16x64_i8 v[54:57], v[150:153], v[190:193], v[54:57]
	v_mfma_i32_16x16x64_i8 v[50:53], v[182:185], v[190:193], v[50:53]
	v_mfma_i32_16x16x64_i8 v[38:41], v[150:153], v[198:201], v[38:41]
	v_mfma_i32_16x16x64_i8 v[34:37], v[182:185], v[198:201], v[34:37]
	v_mfma_i32_16x16x64_i8 v[22:25], v[150:153], v[206:209], v[22:25]
	v_mfma_i32_16x16x64_i8 v[18:21], v[182:185], v[206:209], v[18:21]
	v_mfma_i32_16x16x64_i8 v[6:9], v[150:153], v[214:217], v[6:9]
	v_mfma_i32_16x16x64_i8 v[2:5], v[182:185], v[214:217], v[2:5]
	s_barrier
; #define PG8_STAGE(bufoff, gbase, voff) do { _Pragma("unroll") for (int _i = 0; _i < 2; ++_i) \
;         __builtin_amdgcn_global_load_lds((const unsigned*)((const char*)(gbase) + (voff)[_i]), (LAS unsigned*)(lds + (bufoff) + ldsw + _i * 8192), 16, 0, 0); } while (0)
; #define PG8_LDA(dst, b, h) do { _Pragma("unroll") for (int m = 0; m < 4; ++m) _Pragma("unroll") for (int k = 0; k < 2; ++k) dst[m][k] = *(const LAS bf16x8*)(lds + PG8_SA(b, h) + aoff + m * 2048 + k * 1024); } while (0)
; #define PG8_LDB(dst, b, h) do { _Pragma("unroll") for (int n = 0; n < 2; ++n) _Pragma("unroll") for (int k = 0; k < 2; ++k) dst[n][k] = *(const LAS bf16x8*)(lds + PG8_SB(b, h) + boff + n * 2048 + k * 1024); } while (0)
; #define PG8_WAIT_V(n) asm volatile("s_waitcnt vmcnt(" #n ")" ::: "memory")
; #define PG8_WAIT_L(n) asm volatile("s_waitcnt lgkmcnt(" #n ")" ::: "memory")
; #define PG8_BAR __builtin_amdgcn_s_barrier()
; #define PG8_SCHED __builtin_amdgcn_sched_barrier(0)
; template <class Epi, class Sched, bool I8 = false>
; __device__ __forceinline__ void gemm_phase(LAS unsigned char* lds, const Gemm g, const Sched& S, const Epi& E) {
;     ...
;             PG8_LDB(B0, 1, 0); PG8_LDB(B1, 1, 1); PG8_SCHED; PG8_LDA(At, 1, 0); PG8_STAGE(PG8_SA(0, 1), a2 + hstepA, voffA);
;             PG8_WAIT_V(8); PG8_WAIT_L(0); PG8_BAR; PG8_MMA(0, 0, At, B0); PG8_MMA(0, 1, At, B1); PG8_BAR; PG8_SCHED;
;             PG8_LDA(At, 1, 1); PG8_STAGE(PG8_SB(1, 0), b3, voffB); PG8_STAGE(PG8_SB(1, 1), b3 + hstepB, voffB); PG8_STAGE(PG8_SA(1, 0), a3, voffA);
;             PG8_WAIT_V(8); PG8_WAIT_L(0); PG8_BAR; PG8_MMA(1, 0, At, B0); PG8_MMA(1, 1, At, B1); PG8_BAR; PG8_SCHED;
;         }
	s_add_i32 s52, 0, 0x18000
	s_add_i32 s53, 0, 0x1c000
	v_add_u32_e32 v78, s52, v176
	v_add_u32_e32 v162, s53, v176
	ds_read_b128 v[66:69], v78
	ds_read_b128 v[70:73], v78 offset:1024
	ds_read_b128 v[74:77], v78 offset:2048
	ds_read_b128 v[78:81], v78 offset:3072
	ds_read_b128 v[146:149], v162
	ds_read_b128 v[150:153], v162 offset:1024
	ds_read_b128 v[172:175], v162 offset:2048
	ds_read_b128 v[182:185], v162 offset:3072
	s_mov_b32 m0, s34
	s_nop 0
	global_load_lds_dwordx4 v154, s[26:27]
	s_mov_b32 m0, s35
	s_nop 0
	global_load_lds_dwordx4 v158, s[26:27]
	s_add_u32 s26, s26, 0x4000
	s_addc_u32 s27, s27, 0
	s_mov_b32 m0, s36
	ds_read_b128 v[186:189], v180 offset:32768
	ds_read_b128 v[190:193], v180 offset:33792
	ds_read_b128 v[194:197], v180 offset:34816
	ds_read_b128 v[198:201], v180 offset:35840
	ds_read_b128 v[202:205], v180 offset:36864
	ds_read_b128 v[206:209], v180 offset:37888
	ds_read_b128 v[210:213], v180 offset:38912
	ds_read_b128 v[214:217], v180 offset:39936
	global_load_lds_dwordx4 v154, s[26:27]
	s_mov_b32 m0, s37
	s_nop 0
	global_load_lds_dwordx4 v158, s[26:27]
	s_waitcnt vmcnt(8)
	s_waitcnt lgkmcnt(0)
	s_barrier
	s_waitcnt lgkmcnt(0)
	v_mfma_i32_16x16x64_i8 v[142:145], v[66:69], v[186:189], v[142:145]
	v_mfma_i32_16x16x64_i8 v[138:141], v[74:77], v[186:189], v[138:141]
	v_mfma_i32_16x16x64_i8 v[126:129], v[66:69], v[194:197], v[126:129]
	v_mfma_i32_16x16x64_i8 v[122:125], v[74:77], v[194:197], v[122:125]
	v_mfma_i32_16x16x64_i8 v[110:113], v[66:69], v[202:205], v[110:113]
	v_mfma_i32_16x16x64_i8 v[106:109], v[74:77], v[202:205], v[106:109]
	v_mfma_i32_16x16x64_i8 v[94:97], v[66:69], v[210:213], v[94:97]
	v_mfma_i32_16x16x64_i8 v[90:93], v[74:77], v[210:213], v[90:93]
	v_mfma_i32_16x16x64_i8 v[142:145], v[70:73], v[190:193], v[142:145]
	v_mfma_i32_16x16x64_i8 v[138:141], v[78:81], v[190:193], v[138:141]
	v_mfma_i32_16x16x64_i8 v[126:129], v[70:73], v[198:201], v[126:129]
	v_mfma_i32_16x16x64_i8 v[122:125], v[78:81], v[198:201], v[122:125]
	v_mfma_i32_16x16x64_i8 v[110:113], v[70:73], v[206:209], v[110:113]
	v_mfma_i32_16x16x64_i8 v[106:109], v[78:81], v[206:209], v[106:109]
	v_mfma_i32_16x16x64_i8 v[94:97], v[70:73], v[214:217], v[94:97]
	v_mfma_i32_16x16x64_i8 v[90:93], v[78:81], v[214:217], v[90:93]
	v_mfma_i32_16x16x64_i8 v[134:137], v[146:149], v[186:189], v[134:137]
	v_mfma_i32_16x16x64_i8 v[130:133], v[172:175], v[186:189], v[130:133]
	v_mfma_i32_16x16x64_i8 v[118:121], v[146:149], v[194:197], v[118:121]
	v_mfma_i32_16x16x64_i8 v[114:117], v[172:175], v[194:197], v[114:117]
	v_mfma_i32_16x16x64_i8 v[102:105], v[146:149], v[202:205], v[102:105]
	v_mfma_i32_16x16x64_i8 v[98:101], v[172:175], v[202:205], v[98:101]
	v_mfma_i32_16x16x64_i8 v[86:89], v[146:149], v[210:213], v[86:89]
	v_mfma_i32_16x16x64_i8 v[82:85], v[172:175], v[210:213], v[82:85]
	v_mfma_i32_16x16x64_i8 v[134:137], v[150:153], v[190:193], v[134:137]
	v_mfma_i32_16x16x64_i8 v[130:133], v[182:185], v[190:193], v[130:133]
	v_mfma_i32_16x16x64_i8 v[118:121], v[150:153], v[198:201], v[118:121]
	v_mfma_i32_16x16x64_i8 v[114:117], v[182:185], v[198:201], v[114:117]
	v_mfma_i32_16x16x64_i8 v[102:105], v[150:153], v[206:209], v[102:105]
	v_mfma_i32_16x16x64_i8 v[98:101], v[182:185], v[206:209], v[98:101]
	v_mfma_i32_16x16x64_i8 v[86:89], v[150:153], v[214:217], v[86:89]
	v_mfma_i32_16x16x64_i8 v[82:85], v[182:185], v[214:217], v[82:85]
	s_barrier
	s_add_u32 s26, s24, 0x8000
	s_addc_u32 s27, s25, 0
	s_add_i32 s52, s52, s33
	s_mov_b32 m0, s52
	ds_read_b128 v[186:189], v180 offset:49152
	ds_read_b128 v[190:193], v180 offset:50176
	ds_read_b128 v[194:197], v180 offset:51200
	ds_read_b128 v[198:201], v180 offset:52224
	ds_read_b128 v[202:205], v180 offset:53248
	ds_read_b128 v[206:209], v180 offset:54272
	ds_read_b128 v[210:213], v180 offset:55296
	ds_read_b128 v[214:217], v180 offset:56320
	global_load_lds_dwordx4 v156, s[26:27]
	s_add_i32 m0, s52, 0x2000
	s_add_u32 s24, s24, 0xc000
	v_lshl_add_u64 v[218:219], s[26:27], 0, v[160:161]
	s_addc_u32 s25, s25, 0
	s_add_i32 s26, s53, s33
	global_load_lds_dwordx4 v[218:219], off
	s_mov_b32 m0, s26
	s_nop 0
	global_load_lds_dwordx4 v156, s[24:25]
	s_add_i32 m0, s26, 0x2000
	s_nop 0
	global_load_lds_dwordx4 v160, s[24:25]
	s_waitcnt vmcnt(6)
	s_waitcnt lgkmcnt(0)
	s_barrier
	s_waitcnt lgkmcnt(0)
	v_mfma_i32_16x16x64_i8 v[62:65], v[66:69], v[186:189], v[62:65]
	v_mfma_i32_16x16x64_i8 v[58:61], v[74:77], v[186:189], v[58:61]
	v_mfma_i32_16x16x64_i8 v[46:49], v[66:69], v[194:197], v[46:49]
	v_mfma_i32_16x16x64_i8 v[42:45], v[74:77], v[194:197], v[42:45]
	v_mfma_i32_16x16x64_i8 v[30:33], v[66:69], v[202:205], v[30:33]
	v_mfma_i32_16x16x64_i8 v[26:29], v[74:77], v[202:205], v[26:29]
	v_mfma_i32_16x16x64_i8 v[14:17], v[66:69], v[210:213], v[14:17]
	v_mfma_i32_16x16x64_i8 v[10:13], v[74:77], v[210:213], v[10:13]
	v_mfma_i32_16x16x64_i8 v[62:65], v[70:73], v[190:193], v[62:65]
	v_mfma_i32_16x16x64_i8 v[58:61], v[78:81], v[190:193], v[58:61]
	v_mfma_i32_16x16x64_i8 v[46:49], v[70:73], v[198:201], v[46:49]
	v_mfma_i32_16x16x64_i8 v[42:45], v[78:81], v[198:201], v[42:45]
	v_mfma_i32_16x16x64_i8 v[30:33], v[70:73], v[206:209], v[30:33]
	v_mfma_i32_16x16x64_i8 v[26:29], v[78:81], v[206:209], v[26:29]
	v_mfma_i32_16x16x64_i8 v[14:17], v[70:73], v[214:217], v[14:17]
	v_mfma_i32_16x16x64_i8 v[10:13], v[78:81], v[214:217], v[10:13]
	v_mfma_i32_16x16x64_i8 v[54:57], v[146:149], v[186:189], v[54:57]
	v_mfma_i32_16x16x64_i8 v[50:53], v[172:175], v[186:189], v[50:53]
	v_mfma_i32_16x16x64_i8 v[38:41], v[146:149], v[194:197], v[38:41]
	v_mfma_i32_16x16x64_i8 v[34:37], v[172:175], v[194:197], v[34:37]
	v_mfma_i32_16x16x64_i8 v[22:25], v[146:149], v[202:205], v[22:25]
	v_mfma_i32_16x16x64_i8 v[18:21], v[172:175], v[202:205], v[18:21]
	v_mfma_i32_16x16x64_i8 v[6:9], v[146:149], v[210:213], v[6:9]
	v_mfma_i32_16x16x64_i8 v[2:5], v[172:175], v[210:213], v[2:5]
	v_mfma_i32_16x16x64_i8 v[54:57], v[150:153], v[190:193], v[54:57]
	v_mfma_i32_16x16x64_i8 v[50:53], v[182:185], v[190:193], v[50:53]
	v_mfma_i32_16x16x64_i8 v[38:41], v[150:153], v[198:201], v[38:41]
	v_mfma_i32_16x16x64_i8 v[34:37], v[182:185], v[198:201], v[34:37]
	v_mfma_i32_16x16x64_i8 v[22:25], v[150:153], v[206:209], v[22:25]
	v_mfma_i32_16x16x64_i8 v[18:21], v[182:185], v[206:209], v[18:21]
	v_mfma_i32_16x16x64_i8 v[6:9], v[150:153], v[214:217], v[6:9]
	v_mfma_i32_16x16x64_i8 v[2:5], v[182:185], v[214:217], v[2:5]
	s_add_i32 s51, s51, 2
	s_add_u32 s20, s20, 0x10000
	s_addc_u32 s21, s21, 0
	s_add_u32 s49, s49, 0x10000
	s_addc_u32 s50, s50, 0
	s_cmpk_gt_u32 s51, 0x53
	s_cbranch_scc1 .Lmy_last_6
	s_barrier
	s_branch .LBB0_4168
